# V3 + sample-chain y reduction/store deferred past the chunk barrier + diff-attention epilogue loads de-serialised + permlane swaps for softmax row max
# speedup vs baseline: 1.0231x; 1.0026x over previous
.LBB0_1155:
	ds_bpermute_b32 v34, v114, v84
	s_mov_b32 s0, 0x42b17218
	s_waitcnt lgkmcnt(0)
	v_add_f32_e32 v34, v84, v34
	ds_bpermute_b32 v35, v75, v34
	s_waitcnt lgkmcnt(0)
	v_add_f32_e32 v72, v34, v35
	ds_bpermute_b32 v34, v114, v85
	s_waitcnt lgkmcnt(0)
	v_add_f32_e32 v71, v85, v34
	global_load_dwordx4 v[34:37], v107, s[94:95] offset:48
	global_load_dwordx4 v[38:41], v107, s[94:95] offset:32
	global_load_dwordx4 v[42:45], v107, s[94:95] offset:16
	global_load_dwordx4 v[46:49], v107, s[94:95]
	global_load_dwordx4 v[50:53], v107, s[94:95] offset:176
	global_load_dwordx4 v[54:57], v107, s[94:95] offset:160
	global_load_dwordx4 v[58:61], v107, s[94:95] offset:144
	global_load_dwordx4 v[62:65], v107, s[94:95] offset:128
	global_load_dwordx4 v[66:69], v107, s[94:95] offset:304
	global_load_dwordx4 v[76:79], v107, s[94:95] offset:288
	global_load_dwordx4 v[80:83], v107, s[94:95] offset:272
	global_load_dwordx4 v[88:91], v107, s[94:95] offset:256
	global_load_dwordx4 v[92:95], v107, s[94:95] offset:432
	global_load_dwordx4 v[96:99], v107, s[94:95] offset:416
	global_load_dwordx4 v[100:103], v107, s[94:95] offset:400
	global_load_dwordx4 v[108:111], v107, s[94:95] offset:384
	ds_bpermute_b32 v87, v75, v71
	s_waitcnt vmcnt(8)
	v_fma_f32 v70, v46, v62, 0
	s_waitcnt vmcnt(0)
	v_fma_f32 v73, v88, v108, 0
	v_fmac_f32_e32 v70, v47, v63
	v_fmac_f32_e32 v73, v89, v109
	v_fmac_f32_e32 v70, v48, v64
	v_fmac_f32_e32 v73, v90, v110
	v_fmac_f32_e32 v70, v49, v65
	v_fmac_f32_e32 v73, v91, v111
	v_fmac_f32_e32 v70, v42, v58
	v_fmac_f32_e32 v73, v80, v100
	v_fmac_f32_e32 v70, v43, v59
	v_fmac_f32_e32 v73, v81, v101
	v_fmac_f32_e32 v70, v44, v60
	v_fmac_f32_e32 v73, v82, v102
	v_fmac_f32_e32 v70, v45, v61
	v_fmac_f32_e32 v73, v83, v103
	v_fmac_f32_e32 v70, v38, v54
	v_fmac_f32_e32 v73, v76, v96
	v_fmac_f32_e32 v70, v39, v55
	v_fmac_f32_e32 v73, v77, v97
	v_fmac_f32_e32 v70, v40, v56
	v_fmac_f32_e32 v73, v78, v98
	v_fmac_f32_e32 v70, v41, v57
	v_fmac_f32_e32 v73, v79, v99
	v_fmac_f32_e32 v70, v34, v50
	v_fmac_f32_e32 v73, v66, v92
	v_fmac_f32_e32 v70, v35, v51
	v_fmac_f32_e32 v73, v67, v93
	v_fmac_f32_e32 v70, v36, v52
	v_fmac_f32_e32 v73, v68, v94
	v_fmac_f32_e32 v70, v37, v53
	v_fmac_f32_e32 v73, v69, v95
	global_load_dwordx4 v[62:65], v107, s[94:95] offset:80
	global_load_dwordx4 v[76:79], v107, s[94:95] offset:64
	global_load_dwordx4 v[42:45], v107, s[94:95] offset:112
	global_load_dwordx4 v[50:53], v107, s[94:95] offset:96
	global_load_dwordx4 v[66:69], v107, s[94:95] offset:208
	global_load_dwordx4 v[80:83], v107, s[94:95] offset:192
	global_load_dwordx4 v[46:49], v107, s[94:95] offset:240
	global_load_dwordx4 v[54:57], v107, s[94:95] offset:224
	global_load_dwordx4 v[88:91], v107, s[94:95] offset:336
	global_load_dwordx4 v[92:95], v107, s[94:95] offset:320
	global_load_dwordx4 v[34:37], v107, s[94:95] offset:368
	global_load_dwordx4 v[58:61], v107, s[94:95] offset:352
	global_load_dwordx4 v[96:99], v107, s[94:95] offset:464
	global_load_dwordx4 v[100:103], v107, s[94:95] offset:448
	global_load_dwordx4 v[38:41], v107, s[94:95] offset:496
	global_load_dwordx4 v[108:111], v107, s[94:95] offset:480
	s_waitcnt vmcnt(10)
	v_fmac_f32_e32 v70, v76, v80
	v_fmac_f32_e32 v70, v77, v81
	s_waitcnt vmcnt(2)
	v_fmac_f32_e32 v73, v92, v100
	v_fmac_f32_e32 v70, v78, v82
	v_fmac_f32_e32 v73, v93, v101
	v_fmac_f32_e32 v70, v79, v83
	v_fmac_f32_e32 v73, v94, v102
	v_fmac_f32_e32 v70, v62, v66
	v_fmac_f32_e32 v73, v95, v103
	v_fmac_f32_e32 v70, v63, v67
	v_pk_mul_f32 v[62:63], v[64:65], v[68:69]
	v_fmac_f32_e32 v73, v88, v96
	v_add_f32_e32 v62, v70, v62
	v_fmac_f32_e32 v73, v89, v97
	v_add_f32_e32 v64, v62, v63
	v_pk_mul_f32 v[62:63], v[90:91], v[98:99]
	v_pk_mul_f32 v[50:51], v[50:51], v[54:55]
	v_add_f32_e32 v62, v73, v62
	v_add_f32_e32 v50, v64, v50
	v_add_f32_e32 v62, v62, v63
	v_add_f32_e32 v54, v50, v51
	s_waitcnt vmcnt(0)
	v_pk_mul_f32 v[50:51], v[58:59], v[108:109]
	v_pk_mul_f32 v[42:43], v[42:43], v[46:47]
	v_add_f32_e32 v50, v62, v50
	v_add_f32_e32 v55, v50, v51
	v_pk_mul_f32 v[50:51], v[52:53], v[56:57]
	v_pk_mul_f32 v[34:35], v[34:35], v[38:39]
	v_add_f32_e32 v50, v54, v50
	v_add_f32_e32 v52, v50, v51
	v_pk_mul_f32 v[50:51], v[60:61], v[110:111]
	v_add_f32_e32 v42, v52, v42
	v_add_f32_e32 v50, v55, v50
	v_add_f32_e32 v50, v50, v51
	v_add_f32_e32 v34, v50, v34
	v_add_f32_e32 v42, v42, v43
	v_add_f32_e32 v38, v34, v35
	v_pk_mul_f32 v[34:35], v[44:45], v[48:49]
	s_nop 0
	v_add_f32_e32 v34, v42, v34
	v_add_f32_e32 v39, v34, v35
	v_pk_mul_f32 v[34:35], v[36:37], v[40:41]
	v_cmp_ngt_f32_e32 vcc, s86, v39
	v_add_f32_e32 v34, v38, v34
	v_add_f32_e32 v34, v34, v35
	v_mul_f32_e32 v35, 0x3fb8aa3b, v39
	v_fma_f32 v36, v39, s62, -v35
	v_rndne_f32_e32 v37, v35
	v_fmac_f32_e32 v36, 0x32a5705f, v39
	v_sub_f32_e32 v35, v35, v37
	v_add_f32_e32 v35, v35, v36
	v_exp_f32_e32 v35, v35
	v_cvt_i32_f32_e32 v36, v37
	v_ldexp_f32 v35, v35, v36
	v_mul_f32_e32 v36, 0x3fb8aa3b, v34
	v_fma_f32 v37, v34, s62, -v36
	v_rndne_f32_e32 v38, v36
	v_fmac_f32_e32 v37, 0x32a5705f, v34
	v_sub_f32_e32 v36, v36, v38
	v_add_f32_e32 v36, v36, v37
	v_exp_f32_e32 v36, v36
	v_cvt_i32_f32_e32 v37, v38
	v_cndmask_b32_e32 v35, 0, v35, vcc
	v_cmp_nlt_f32_e32 vcc, s0, v39
	v_ldexp_f32 v36, v36, v37
	s_nop 0
	v_cndmask_b32_e32 v35, v148, v35, vcc
	v_cmp_ngt_f32_e32 vcc, s86, v34
	s_nop 1
	v_cndmask_b32_e32 v36, 0, v36, vcc
	v_cmp_nlt_f32_e32 vcc, s0, v34
	v_readlane_b32 s0, v206, 63
	v_readlane_b32 s1, v205, 0
	v_cndmask_b32_e32 v34, v148, v36, vcc
	v_div_scale_f32 v36, s[12:13], v72, v72, 1.0
	v_rcp_f32_e32 v37, v36
	v_sub_f32_e32 v70, v35, v34
	s_waitcnt lgkmcnt(0)
	v_pk_add_f32 v[34:35], v[86:87], v[70:71]
	v_fma_f32 v38, -v36, v37, 1.0
	v_fmac_f32_e32 v37, v38, v37
	v_div_scale_f32 v38, vcc, 1.0, v72, 1.0
	v_mul_f32_e32 v39, v38, v37
	v_fma_f32 v40, -v36, v39, v38
	v_fmac_f32_e32 v39, v40, v37
	v_fma_f32 v36, -v36, v39, v38
	v_div_fmas_f32 v36, v36, v37, v39
	v_div_fixup_f32 v38, v36, v72, 1.0
	v_div_scale_f32 v36, s[12:13], v35, v35, v34
	v_rcp_f32_e32 v37, v36
	s_nop 0
	v_fma_f32 v39, -v36, v37, 1.0
	v_fmac_f32_e32 v37, v39, v37
	v_div_scale_f32 v39, vcc, v34, v35, v34
	v_mul_f32_e32 v40, v39, v37
	v_fma_f32 v41, -v36, v40, v39
	v_fmac_f32_e32 v40, v41, v37
	v_fma_f32 v36, -v36, v40, v39
	v_div_fmas_f32 v36, v36, v37, v40
	v_div_fixup_f32 v40, v36, v35, v34
	v_pk_mul_f32 v[2:3], v[2:3], v[40:41] op_sel_hi:[1,0]
	v_pk_mul_f32 v[4:5], v[4:5], v[40:41] op_sel_hi:[1,0]
	v_pk_fma_f32 v[36:37], v[6:7], v[38:39], v[2:3] op_sel_hi:[1,0,1] neg_lo:[0,0,1] neg_hi:[0,0,1]
	v_pk_mul_f32 v[2:3], v[14:15], v[40:41] op_sel_hi:[1,0]
	v_pk_fma_f32 v[34:35], v[8:9], v[38:39], v[4:5] op_sel_hi:[1,0,1] neg_lo:[0,0,1] neg_hi:[0,0,1]
	v_pk_mul_f32 v[4:5], v[16:17], v[40:41] op_sel_hi:[1,0]
	v_pk_fma_f32 v[10:11], v[10:11], v[38:39], v[2:3] op_sel_hi:[1,0,1] neg_lo:[0,0,1] neg_hi:[0,0,1]
	v_pk_fma_f32 v[12:13], v[12:13], v[38:39], v[4:5] op_sel_hi:[1,0,1] neg_lo:[0,0,1] neg_hi:[0,0,1]
	v_mov_b32_e32 v4, v37
	v_mov_b32_e32 v5, v11
	v_mov_b32_e32 v2, v36
	v_mov_b32_e32 v3, v10
	v_pk_mul_f32 v[4:5], v[4:5], v[4:5]
	v_pk_mul_f32 v[6:7], v[24:25], v[40:41] op_sel_hi:[1,0]
	v_pk_fma_f32 v[2:3], v[2:3], v[2:3], v[4:5]
	v_mov_b32_e32 v4, v34
	v_mov_b32_e32 v5, v12
	v_pk_fma_f32 v[2:3], v[4:5], v[4:5], v[2:3]
	v_mov_b32_e32 v4, v35
	v_mov_b32_e32 v5, v13
	v_pk_fma_f32 v[2:3], v[4:5], v[4:5], v[2:3]
	v_pk_mul_f32 v[4:5], v[22:23], v[40:41] op_sel_hi:[1,0]
	v_pk_fma_f32 v[14:15], v[20:21], v[38:39], v[6:7] op_sel_hi:[1,0,1] neg_lo:[0,0,1] neg_hi:[0,0,1]
	v_pk_fma_f32 v[16:17], v[18:19], v[38:39], v[4:5] op_sel_hi:[1,0,1] neg_lo:[0,0,1] neg_hi:[0,0,1]
	v_pk_mul_f32 v[4:5], v[30:31], v[40:41] op_sel_hi:[1,0]
	v_pk_mul_f32 v[6:7], v[32:33], v[40:41] op_sel_hi:[1,0]
	v_pk_fma_f32 v[8:9], v[26:27], v[38:39], v[4:5] op_sel_hi:[1,0,1] neg_lo:[0,0,1] neg_hi:[0,0,1]
	v_mov_b32_e32 v19, v17
	v_mov_b32_e32 v18, v9
	v_pk_fma_f32 v[6:7], v[28:29], v[38:39], v[6:7] op_sel_hi:[1,0,1] neg_lo:[0,0,1] neg_hi:[0,0,1]
	v_mov_b32_e32 v4, v8
	v_mov_b32_e32 v5, v16
	v_pk_mul_f32 v[18:19], v[18:19], v[18:19]
	v_add_f32_e32 v2, v2, v3
	v_pk_fma_f32 v[4:5], v[4:5], v[4:5], v[18:19]
	v_mov_b32_e32 v18, v6
	v_mov_b32_e32 v19, v14
	v_pk_fma_f32 v[4:5], v[18:19], v[18:19], v[4:5]
	v_mov_b32_e32 v18, v7
	v_mov_b32_e32 v19, v15
	v_pk_fma_f32 v[4:5], v[18:19], v[18:19], v[4:5]
	s_nop 0
	v_add_f32_e32 v2, v5, v2
	v_add_f32_e32 v3, v4, v2
	v_add_u32_e32 v2, s39, v1
	ds_bpermute_b32 v1, v114, v3
	s_waitcnt lgkmcnt(0)
	v_add_f32_e32 v1, v3, v1
	ds_bpermute_b32 v3, v75, v1
	v_mov_b32_e32 v75, v107
	s_waitcnt lgkmcnt(0)
	v_add_f32_e32 v1, v1, v3
	v_fmamk_f32 v1, v1, 0x3c800000, v139
	v_cmp_gt_f32_e32 vcc, s56, v1
	v_mul_f32_e32 v3, 0x4b800000, v1
	s_nop 0
	v_cndmask_b32_e32 v1, v1, v3, vcc
	v_rsq_f32_e32 v1, v1
	s_nop 0
	v_mul_f32_e32 v3, 0x45800000, v1
	v_cndmask_b32_e32 v1, v1, v3, vcc
	v_ashrrev_i32_e32 v3, 31, v2
	v_lshlrev_b64 v[20:21], 10, v[2:3]
	global_load_dwordx4 v[2:5], v74, s[28:29]
	global_load_dwordx4 v[232:235], v74, s[28:29] offset:64
	global_load_dwordx4 v[236:239], v74, s[28:29] offset:128
	global_load_dwordx4 v[240:243], v74, s[28:29] offset:192
	v_mul_f32_e32 v18, v113, v1
	v_pk_mul_f32 v[22:23], v[36:37], v[18:19] op_sel_hi:[1,0]
	v_pk_mul_f32 v[24:25], v[34:35], v[18:19] op_sel_hi:[1,0]
	v_lshl_add_u64 v[20:21], s[0:1], 0, v[20:21]
	v_lshl_add_u64 v[20:21], v[20:21], 0, v[74:75]
	v_pk_mul_f32 v[12:13], v[12:13], v[18:19] op_sel_hi:[1,0]
	v_pk_mul_f32 v[10:11], v[10:11], v[18:19] op_sel_hi:[1,0]
	v_pk_mul_f32 v[6:7], v[6:7], v[18:19] op_sel_hi:[1,0]
	v_pk_mul_f32 v[8:9], v[8:9], v[18:19] op_sel_hi:[1,0]
	s_waitcnt vmcnt(0)
	v_pk_mul_f32 v[4:5], v[4:5], v[24:25]
	v_pk_mul_f32 v[2:3], v[2:3], v[22:23]
	v_pk_mul_f32 v[232:233], v[232:233], v[10:11]
	global_store_dwordx4 v[20:21], v[2:5], off
	v_pk_mul_f32 v[234:235], v[234:235], v[12:13]
	s_nop 0
	v_pk_mul_f32 v[10:11], v[14:15], v[18:19] op_sel_hi:[1,0]
	v_pk_mul_f32 v[12:13], v[16:17], v[18:19] op_sel_hi:[1,0]
	global_store_dwordx4 v[20:21], v[232:235], off offset:64
	v_pk_mul_f32 v[238:239], v[238:239], v[10:11]
	v_pk_mul_f32 v[240:241], v[240:241], v[8:9]
	v_pk_mul_f32 v[236:237], v[236:237], v[12:13]
	v_pk_mul_f32 v[242:243], v[242:243], v[6:7]
	global_store_dwordx4 v[20:21], v[236:239], off offset:128
	global_store_dwordx4 v[20:21], v[240:243], off offset:192

.LBB0_1163:
	s_add_i32 s12, s13, 1
	s_bitcmp1_b32 s13, 0
	s_cselect_b32 s13, 0x4800, 0
	v_or_b32_e32 v80, s13, v42
	v_add_u32_e32 v55, v80, v47
	ds_read_b128 v[56:59], v55
	ds_read_b128 v[60:63], v55 offset:64
	v_add_u32_e32 v84, v80, v53
	ds_read_b128 v[80:83], v84 offset:9216
	s_andn2_b64 vcc, exec, s[60:61]
	s_waitcnt lgkmcnt(2)
	v_mfma_f32_16x16x32_bf16 v[56:59], v[56:59], v[2:5], 0
	ds_read_b128 v[64:67], v55 offset:640
	ds_read_b128 v[68:71], v55 offset:4672
	ds_read_b128 v[72:75], v55 offset:5248
	s_waitcnt lgkmcnt(4)
	v_mfma_f32_16x16x32_bf16 v[56:59], v[60:63], v[6:9], v[56:59]
	ds_read_b128 v[60:63], v55 offset:576
	s_waitcnt lgkmcnt(0)
	v_mfma_f32_16x16x32_bf16 v[60:63], v[60:63], v[2:5], 0
	v_mfma_f32_16x16x32_bf16 v[60:63], v[64:67], v[6:9], v[60:63]
	ds_read_b128 v[64:67], v55 offset:4608
	s_waitcnt lgkmcnt(0)
	v_mfma_f32_16x16x32_bf16 v[64:67], v[64:67], v[2:5], 0
	v_mfma_f32_16x16x32_bf16 v[64:67], v[68:71], v[6:9], v[64:67]
	ds_read_b128 v[68:71], v55 offset:5184
	v_mul_f32_e32 v55, 0x3e38aa3b, v56
	s_waitcnt lgkmcnt(0)
	v_mfma_f32_16x16x32_bf16 v[68:71], v[68:71], v[2:5], 0
	v_mfma_f32_16x16x32_bf16 v[68:71], v[72:75], v[6:9], v[68:71]
	v_mul_f32_e32 v72, 0x3e38aa3b, v57
	v_max3_f32 v55, v55, s88, v72
	v_mul_f32_e32 v72, 0x3e38aa3b, v58
	v_mul_f32_e32 v73, 0x3e38aa3b, v59
	v_max3_f32 v55, v55, v72, v73
	v_mul_f32_e32 v72, 0x3e38aa3b, v60
	v_mul_f32_e32 v73, 0x3e38aa3b, v61
	v_max3_f32 v55, v55, v72, v73
	v_mul_f32_e32 v72, 0x3e38aa3b, v62
	v_mul_f32_e32 v73, 0x3e38aa3b, v63
	v_max3_f32 v55, v55, v72, v73
	v_mul_f32_e32 v72, 0x3e38aa3b, v64
	v_mul_f32_e32 v73, 0x3e38aa3b, v65
	v_max3_f32 v55, v55, v72, v73
	v_mul_f32_e32 v72, 0x3e38aa3b, v66
	v_mul_f32_e32 v73, 0x3e38aa3b, v67
	v_max3_f32 v55, v55, v72, v73
	v_mul_f32_e32 v72, 0x3e38aa3b, v68
	v_mul_f32_e32 v73, 0x3e38aa3b, v69
	v_max3_f32 v55, v55, v72, v73
	v_mul_f32_e32 v72, 0x3e38aa3b, v70
	v_mul_f32_e32 v73, 0x3e38aa3b, v71
	v_max3_f32 v55, v55, v72, v73
	v_mov_b32_e32 v252, v55
	v_mov_b32_e32 v253, v55
	s_nop 1
	v_permlane16_swap_b32_e32 v252, v253
	s_waitcnt lgkmcnt(0)
	v_max_f32_e32 v55, v252, v253
	v_mov_b32_e32 v254, v55
	v_mov_b32_e32 v255, v55
	s_nop 1
	v_permlane32_swap_b32_e32 v254, v255
	s_waitcnt lgkmcnt(0)
	v_max3_f32 v55, v52, v254, v255
	v_sub_f32_e32 v52, v52, v55
	v_fma_f32 v56, v56, s91, -v55
	v_fma_f32 v57, v57, s91, -v55
	v_fma_f32 v58, v58, s91, -v55
	v_fma_f32 v59, v59, s91, -v55
	v_fma_f32 v60, v60, s91, -v55
	v_fma_f32 v61, v61, s91, -v55
	v_fma_f32 v62, v62, s91, -v55
	v_fma_f32 v63, v63, s91, -v55
	v_exp_f32_e32 v52, v52
	v_exp_f32_e32 v56, v56
	v_exp_f32_e32 v57, v57
	v_exp_f32_e32 v58, v58
	v_exp_f32_e32 v59, v59
	v_exp_f32_e32 v60, v60
	v_exp_f32_e32 v61, v61
	v_exp_f32_e32 v62, v62
	v_exp_f32_e32 v63, v63
	v_pk_mul_f32 v[28:29], v[28:29], v[52:53] op_sel_hi:[1,0]
	v_pk_mul_f32 v[26:27], v[26:27], v[52:53] op_sel_hi:[1,0]
	v_cvt_pk_bf16_f32 v72, v56, v57
	v_cvt_pk_bf16_f32 v73, v58, v59
	v_cvt_pk_bf16_f32 v74, v60, v61
	v_cvt_pk_bf16_f32 v75, v62, v63
	v_fma_f32 v64, v64, s91, -v55
	v_fma_f32 v65, v65, s91, -v55
	v_mfma_f32_16x16x32_bf16 v[26:29], v[80:83], v[72:75], v[26:29]
	ds_read_b128 v[80:83], v84 offset:9280
	v_fma_f32 v66, v66, s91, -v55
	v_fma_f32 v67, v67, s91, -v55
	v_fma_f32 v68, v68, s91, -v55
	v_fma_f32 v69, v69, s91, -v55
	v_fma_f32 v70, v70, s91, -v55
	v_fma_f32 v71, v71, s91, -v55
	v_exp_f32_e32 v64, v64
	v_exp_f32_e32 v65, v65
	v_exp_f32_e32 v66, v66
	v_exp_f32_e32 v67, v67
	v_exp_f32_e32 v68, v68
	v_exp_f32_e32 v69, v69
	v_exp_f32_e32 v70, v70
	v_exp_f32_e32 v71, v71
	v_cvt_pk_bf16_f32 v76, v64, v65
	v_cvt_pk_bf16_f32 v77, v66, v67
	v_cvt_pk_bf16_f32 v78, v68, v69
	v_cvt_pk_bf16_f32 v79, v70, v71
	v_pk_mul_f32 v[32:33], v[32:33], v[52:53] op_sel_hi:[1,0]
	v_pk_mul_f32 v[30:31], v[30:31], v[52:53] op_sel_hi:[1,0]
	s_waitcnt lgkmcnt(0)
	v_mfma_f32_16x16x32_bf16 v[26:29], v[80:83], v[76:79], v[26:29]
	ds_read_b128 v[80:83], v84 offset:11520
	v_pk_mul_f32 v[36:37], v[36:37], v[52:53] op_sel_hi:[1,0]
	v_pk_mul_f32 v[34:35], v[34:35], v[52:53] op_sel_hi:[1,0]
	s_waitcnt lgkmcnt(0)
	v_mfma_f32_16x16x32_bf16 v[30:33], v[80:83], v[72:75], v[30:33]
	ds_read_b128 v[80:83], v84 offset:11584
	v_pk_mul_f32 v[40:41], v[40:41], v[52:53] op_sel_hi:[1,0]
	v_pk_mul_f32 v[38:39], v[38:39], v[52:53] op_sel_hi:[1,0]
	s_waitcnt lgkmcnt(0)
	v_mfma_f32_16x16x32_bf16 v[30:33], v[80:83], v[76:79], v[30:33]
	ds_read_b128 v[80:83], v84 offset:13824
	s_waitcnt lgkmcnt(0)
	v_mfma_f32_16x16x32_bf16 v[34:37], v[80:83], v[72:75], v[34:37]
	ds_read_b128 v[80:83], v84 offset:13888
	s_waitcnt lgkmcnt(0)
	v_mfma_f32_16x16x32_bf16 v[34:37], v[80:83], v[76:79], v[34:37]
	ds_read_b128 v[80:83], v84 offset:16128
	s_waitcnt lgkmcnt(0)
	v_mfma_f32_16x16x32_bf16 v[38:41], v[80:83], v[72:75], v[38:41]
	ds_read_b128 v[72:75], v84 offset:16192
	s_waitcnt lgkmcnt(0)
	v_mfma_f32_16x16x32_bf16 v[38:41], v[72:75], v[76:79], v[38:41]
	s_cbranch_vccnz .LBB0_1165
	s_bitcmp1_b32 s12, 0
	s_cselect_b32 s13, 0x4800, 0
	v_add_u32_e32 v72, s13, v46
	s_waitcnt vmcnt(3)
	ds_write_b128 v72, v[14:17]
	s_waitcnt vmcnt(2)
	ds_write_b128 v72, v[10:13] offset:16
	s_waitcnt vmcnt(0)
	ds_write_b128 v72, v[22:25] offset:9216
	ds_write_b128 v72, v[18:21] offset:9232

.LBB0_1173:
	s_add_i32 s68, s12, 1
	s_bitcmp1_b32 s12, 0
	s_cselect_b32 s12, 0x4800, 0
	v_or_b32_e32 v99, s12, v74
	v_add_u32_e32 v93, v99, v81
	ds_read_b128 v[62:65], v93
	ds_read_b128 v[66:69], v93 offset:576
	ds_read_b128 v[70:73], v93 offset:4608
	ds_read_b128 v[88:91], v93 offset:5184
	s_andn2_b64 vcc, exec, s[60:61]
	s_waitcnt vmcnt(1) lgkmcnt(3)
	v_mfma_f32_16x16x32_bf16 v[62:65], v[62:65], v[50:53], 0
	s_waitcnt lgkmcnt(2)
	v_mfma_f32_16x16x32_bf16 v[66:69], v[66:69], v[50:53], 0
	s_nop 5
	v_mul_f32_e32 v59, 0x3e8293ee, v62
	v_mul_f32_e32 v60, 0x3e8293ee, v63
	v_max3_f32 v59, v59, s88, v60
	s_waitcnt lgkmcnt(1)
	v_mfma_f32_16x16x32_bf16 v[70:73], v[70:73], v[50:53], 0
	v_mul_f32_e32 v60, 0x3e8293ee, v64
	s_waitcnt lgkmcnt(0)
	v_mfma_f32_16x16x32_bf16 v[122:125], v[88:91], v[50:53], 0
	v_mul_f32_e32 v88, 0x3e8293ee, v65
	v_max3_f32 v59, v59, v60, v88
	v_mul_f32_e32 v60, 0x3e8293ee, v66
	v_mul_f32_e32 v88, 0x3e8293ee, v67
	v_max3_f32 v59, v59, v60, v88
	v_mul_f32_e32 v60, 0x3e8293ee, v68
	v_mul_f32_e32 v88, 0x3e8293ee, v69
	v_max3_f32 v59, v59, v60, v88
	v_mul_f32_e32 v60, 0x3e8293ee, v70
	v_mul_f32_e32 v88, 0x3e8293ee, v71
	v_max3_f32 v59, v59, v60, v88
	v_mul_f32_e32 v60, 0x3e8293ee, v72
	v_mul_f32_e32 v88, 0x3e8293ee, v73
	v_max3_f32 v59, v59, v60, v88
	v_mul_f32_e32 v60, 0x3e8293ee, v122
	v_mul_f32_e32 v88, 0x3e8293ee, v123
	v_max3_f32 v59, v59, v60, v88
	v_mul_f32_e32 v60, 0x3e8293ee, v124
	v_mul_f32_e32 v88, 0x3e8293ee, v125
	v_max3_f32 v59, v59, v60, v88
	v_mov_b32_e32 v252, v59
	v_mov_b32_e32 v253, v59
	s_nop 1
	v_permlane16_swap_b32_e32 v252, v253
	s_waitcnt lgkmcnt(0)
	v_max_f32_e32 v59, v252, v253
	v_mov_b32_e32 v254, v59
	v_mov_b32_e32 v255, v59
	s_nop 1
	v_permlane32_swap_b32_e32 v254, v255
	s_waitcnt lgkmcnt(0)
	v_max3_f32 v114, v58, v254, v255
	v_fma_f32 v59, v62, s89, -v114
	v_exp_f32_e32 v115, v59
	v_fma_f32 v59, v63, s89, -v114
	v_exp_f32_e32 v116, v59
	v_fma_f32 v59, v64, s89, -v114
	v_exp_f32_e32 v117, v59
	v_fma_f32 v59, v65, s89, -v114
	v_exp_f32_e32 v118, v59
	v_fma_f32 v59, v66, s89, -v114
	v_exp_f32_e32 v119, v59
	v_fma_f32 v59, v67, s89, -v114
	v_exp_f32_e32 v120, v59
	v_fma_f32 v59, v68, s89, -v114
	v_exp_f32_e32 v96, v59
	v_fma_f32 v59, v69, s89, -v114
	v_exp_f32_e32 v110, v59
	v_fma_f32 v59, v70, s89, -v114
	v_exp_f32_e32 v94, v59
	v_fma_f32 v59, v71, s89, -v114
	ds_read_b128 v[62:65], v93 offset:64
	ds_read_b128 v[66:69], v93 offset:640
	v_exp_f32_e32 v108, v59
	v_fma_f32 v59, v72, s89, -v114
	v_exp_f32_e32 v92, v59
	v_fma_f32 v59, v73, s89, -v114
	v_exp_f32_e32 v104, v59
	v_fma_f32 v59, v122, s89, -v114
	v_exp_f32_e32 v90, v59
	v_fma_f32 v59, v123, s89, -v114
	ds_read_b128 v[70:73], v93 offset:4672
	v_exp_f32_e32 v102, v59
	v_fma_f32 v59, v124, s89, -v114
	v_exp_f32_e32 v88, v59
	v_fma_f32 v59, v125, s89, -v114
	ds_read_b128 v[122:125], v93 offset:5248
	s_waitcnt vmcnt(0) lgkmcnt(3)
	v_mfma_f32_16x16x32_bf16 v[62:65], v[62:65], v[54:57], 0
	v_sub_f32_e32 v58, v58, v114
	v_exp_f32_e32 v98, v58
	v_exp_f32_e32 v100, v59
	s_waitcnt lgkmcnt(2)
	v_mfma_f32_16x16x32_bf16 v[66:69], v[66:69], v[54:57], 0
	v_cvt_pk_bf16_f32 v58, v115, v116
	s_nop 1
	v_mul_f32_e32 v89, 0x3e8293ee, v62
	v_mul_f32_e32 v91, 0x3e8293ee, v63
	s_waitcnt lgkmcnt(1)
	v_mfma_f32_16x16x32_bf16 v[70:73], v[70:73], v[54:57], 0
	v_max3_f32 v89, v89, s88, v91
	v_mul_f32_e32 v91, 0x3e8293ee, v64
	v_mul_f32_e32 v93, 0x3e8293ee, v65
	s_waitcnt lgkmcnt(0)
	v_mfma_f32_16x16x32_bf16 v[128:131], v[122:125], v[54:57], 0
	v_max3_f32 v89, v89, v91, v93
	v_mul_f32_e32 v91, 0x3e8293ee, v66
	v_mul_f32_e32 v93, 0x3e8293ee, v67
	v_max3_f32 v89, v89, v91, v93
	v_mul_f32_e32 v91, 0x3e8293ee, v68
	v_mul_f32_e32 v93, 0x3e8293ee, v69
	v_max3_f32 v89, v89, v91, v93
	v_mul_f32_e32 v91, 0x3e8293ee, v70
	v_mul_f32_e32 v93, 0x3e8293ee, v71
	v_max3_f32 v89, v89, v91, v93
	v_mul_f32_e32 v91, 0x3e8293ee, v72
	v_mul_f32_e32 v93, 0x3e8293ee, v73
	v_max3_f32 v89, v89, v91, v93
	v_mul_f32_e32 v91, 0x3e8293ee, v128
	v_mul_f32_e32 v93, 0x3e8293ee, v129
	v_max3_f32 v89, v89, v91, v93
	v_mul_f32_e32 v91, 0x3e8293ee, v130
	v_mul_f32_e32 v93, 0x3e8293ee, v131
	v_max3_f32 v89, v89, v91, v93
	v_mov_b32_e32 v252, v89
	v_mov_b32_e32 v253, v89
	s_nop 1
	v_permlane16_swap_b32_e32 v252, v253
	v_pk_mul_f32 v[4:5], v[4:5], v[98:99] op_sel_hi:[1,0]
	v_pk_mul_f32 v[2:3], v[2:3], v[98:99] op_sel_hi:[1,0]
	v_pk_mul_f32 v[12:13], v[12:13], v[98:99] op_sel_hi:[1,0]
	v_pk_mul_f32 v[10:11], v[10:11], v[98:99] op_sel_hi:[1,0]
	s_waitcnt lgkmcnt(0)
	v_max_f32_e32 v89, v252, v253
	v_mov_b32_e32 v254, v89
	v_mov_b32_e32 v255, v89
	s_nop 1
	v_permlane32_swap_b32_e32 v254, v255
	v_pk_mul_f32 v[16:17], v[16:17], v[98:99] op_sel_hi:[1,0]
	v_pk_mul_f32 v[14:15], v[14:15], v[98:99] op_sel_hi:[1,0]
	v_cvt_pk_bf16_f32 v59, v117, v118
	v_cvt_pk_bf16_f32 v60, v119, v120
	s_waitcnt lgkmcnt(0)
	v_max3_f32 v121, v61, v254, v255
	v_fma_f32 v62, v62, s89, -v121
	v_exp_f32_e32 v122, v62
	v_fma_f32 v62, v63, s89, -v121
	v_exp_f32_e32 v123, v62
	v_fma_f32 v62, v64, s89, -v121
	v_exp_f32_e32 v124, v62
	v_fma_f32 v62, v65, s89, -v121
	v_exp_f32_e32 v125, v62
	v_fma_f32 v62, v66, s89, -v121
	v_exp_f32_e32 v126, v62
	v_fma_f32 v62, v67, s89, -v121
	v_exp_f32_e32 v127, v62
	v_fma_f32 v62, v68, s89, -v121
	v_exp_f32_e32 v97, v62
	v_fma_f32 v62, v69, s89, -v121
	v_exp_f32_e32 v111, v62
	v_fma_f32 v62, v70, s89, -v121
	v_exp_f32_e32 v95, v62
	v_fma_f32 v62, v71, s89, -v121
	v_exp_f32_e32 v109, v62
	v_fma_f32 v62, v72, s89, -v121
	v_exp_f32_e32 v93, v62
	v_fma_f32 v62, v73, s89, -v121
	v_exp_f32_e32 v105, v62
	v_fma_f32 v62, v128, s89, -v121
	v_exp_f32_e32 v91, v62
	v_fma_f32 v62, v129, s89, -v121
	v_exp_f32_e32 v103, v62
	v_fma_f32 v62, v130, s89, -v121
	v_exp_f32_e32 v89, v62
	v_fma_f32 v62, v131, s89, -v121
	v_exp_f32_e32 v101, v62
	v_pk_mul_f32 v[64:65], v[20:21], v[98:99] op_sel_hi:[1,0]
	v_pk_mul_f32 v[62:63], v[18:19], v[98:99] op_sel_hi:[1,0]
	v_add_u32_e32 v99, v99, v87
	ds_read_b128 v[128:131], v99 offset:9216
	v_sub_f32_e32 v61, v61, v121
	v_exp_f32_e32 v112, v61
	v_cvt_pk_bf16_f32 v61, v96, v110
	v_cvt_pk_bf16_f32 v70, v122, v123
	v_cvt_pk_bf16_f32 v71, v124, v125
	v_pk_mul_f32 v[8:9], v[8:9], v[112:113] op_sel_hi:[1,0]
	v_pk_mul_f32 v[6:7], v[6:7], v[112:113] op_sel_hi:[1,0]
	v_cvt_pk_bf16_f32 v72, v126, v127
	v_cvt_pk_bf16_f32 v73, v97, v111
	s_waitcnt lgkmcnt(0)
	v_mfma_f32_16x16x32_bf16 v[2:5], v[128:131], v[58:61], v[2:5]
	v_cvt_pk_bf16_f32 v18, v94, v108
	v_cvt_pk_bf16_f32 v19, v92, v104
	v_cvt_pk_bf16_f32 v20, v90, v102
	v_mfma_f32_16x16x32_bf16 v[6:9], v[128:131], v[70:73], v[6:9]
	ds_read_b128 v[128:131], v99 offset:9280
	v_cvt_pk_bf16_f32 v21, v88, v100
	v_pk_mul_f32 v[68:69], v[32:33], v[112:113] op_sel_hi:[1,0]
	v_pk_mul_f32 v[66:67], v[30:31], v[112:113] op_sel_hi:[1,0]
	v_cvt_pk_bf16_f32 v30, v95, v109
	v_cvt_pk_bf16_f32 v31, v93, v105
	v_cvt_pk_bf16_f32 v32, v91, v103
	v_cvt_pk_bf16_f32 v33, v89, v101
	s_waitcnt lgkmcnt(0)
	v_mfma_f32_16x16x32_bf16 v[2:5], v[128:131], v[18:21], v[2:5]
	v_mul_f32_e64 v24, v24, v112
	v_mul_f32_e64 v25, v25, v112
	v_pk_mul_f32 v[22:23], v[22:23], v[112:113] op_sel_hi:[1,0]
	v_pk_mul_f32 v[28:29], v[28:29], v[112:113] op_sel_hi:[1,0]
	v_mfma_f32_16x16x32_bf16 v[6:9], v[128:131], v[30:33], v[6:9]
	ds_read_b128 v[128:131], v99 offset:11520
	v_pk_mul_f32 v[26:27], v[26:27], v[112:113] op_sel_hi:[1,0]
	s_waitcnt lgkmcnt(0)
	v_mfma_f32_16x16x32_bf16 v[10:13], v[128:131], v[58:61], v[10:13]
	v_mfma_f32_16x16x32_bf16 v[22:25], v[128:131], v[70:73], v[22:25]
	ds_read_b128 v[128:131], v99 offset:11584
	s_waitcnt lgkmcnt(0)
	v_mfma_f32_16x16x32_bf16 v[10:13], v[128:131], v[18:21], v[10:13]
	v_mfma_f32_16x16x32_bf16 v[22:25], v[128:131], v[30:33], v[22:25]
	ds_read_b128 v[128:131], v99 offset:13824
	s_waitcnt lgkmcnt(0)
	v_mfma_f32_16x16x32_bf16 v[14:17], v[128:131], v[58:61], v[14:17]
	v_mfma_f32_16x16x32_bf16 v[26:29], v[128:131], v[70:73], v[26:29]
	ds_read_b128 v[128:131], v99 offset:13888
	s_waitcnt lgkmcnt(0)
	v_mfma_f32_16x16x32_bf16 v[14:17], v[128:131], v[18:21], v[14:17]
	v_mfma_f32_16x16x32_bf16 v[26:29], v[128:131], v[30:33], v[26:29]
	ds_read_b128 v[128:131], v99 offset:16128
	s_waitcnt lgkmcnt(0)
	v_mfma_f32_16x16x32_bf16 v[58:61], v[128:131], v[58:61], v[62:65]
	v_mfma_f32_16x16x32_bf16 v[62:65], v[128:131], v[70:73], v[66:69]
	s_nop 2
	ds_read_b128 v[66:69], v99 offset:16192
	s_waitcnt lgkmcnt(0)
	v_mfma_f32_16x16x32_bf16 v[18:21], v[66:69], v[18:21], v[58:61]
	v_mfma_f32_16x16x32_bf16 v[30:33], v[66:69], v[30:33], v[62:65]
	s_cbranch_vccnz .LBB0_1170
	s_bitcmp1_b32 s68, 0
	s_cselect_b32 s12, 0x4800, 0
	v_add_u32_e32 v58, s12, v80
	ds_write_b128 v58, v[34:37]
	ds_write_b128 v58, v[38:41] offset:16
	ds_write_b128 v58, v[42:45] offset:9216
	ds_write_b128 v58, v[46:49] offset:9232
	s_branch .LBB0_1170
.LBB0_1175:
	ds_bpermute_b32 v34, v75, v84
	s_mov_b32 s0, 0x42b17218
	s_waitcnt lgkmcnt(0)
	v_add_f32_e32 v34, v84, v34
	ds_bpermute_b32 v35, v1, v34
	s_waitcnt lgkmcnt(0)
	v_add_f32_e32 v72, v34, v35
	ds_bpermute_b32 v34, v75, v85
	s_waitcnt lgkmcnt(0)
	v_add_f32_e32 v71, v85, v34
	global_load_dwordx4 v[34:37], v107, s[94:95] offset:48
	global_load_dwordx4 v[38:41], v107, s[94:95] offset:32
	global_load_dwordx4 v[42:45], v107, s[94:95] offset:16
	global_load_dwordx4 v[46:49], v107, s[94:95]
	global_load_dwordx4 v[50:53], v107, s[94:95] offset:176
	global_load_dwordx4 v[54:57], v107, s[94:95] offset:160
	global_load_dwordx4 v[58:61], v107, s[94:95] offset:144
	global_load_dwordx4 v[62:65], v107, s[94:95] offset:128
	global_load_dwordx4 v[66:69], v107, s[94:95] offset:304
	global_load_dwordx4 v[78:81], v107, s[94:95] offset:288
	global_load_dwordx4 v[82:85], v107, s[94:95] offset:272
	global_load_dwordx4 v[88:91], v107, s[94:95] offset:256
	global_load_dwordx4 v[92:95], v107, s[94:95] offset:432
	global_load_dwordx4 v[96:99], v107, s[94:95] offset:416
	global_load_dwordx4 v[100:103], v107, s[94:95] offset:400
	global_load_dwordx4 v[108:111], v107, s[94:95] offset:384
	ds_bpermute_b32 v87, v1, v71
	s_waitcnt vmcnt(8)
	v_fma_f32 v70, v46, v62, 0
	s_waitcnt vmcnt(0)
	v_fma_f32 v73, v88, v108, 0
	v_fmac_f32_e32 v70, v47, v63
	v_fmac_f32_e32 v73, v89, v109
	v_fmac_f32_e32 v70, v48, v64
	v_fmac_f32_e32 v73, v90, v110
	v_fmac_f32_e32 v70, v49, v65
	v_fmac_f32_e32 v73, v91, v111
	v_fmac_f32_e32 v70, v42, v58
	v_fmac_f32_e32 v73, v82, v100
	v_fmac_f32_e32 v70, v43, v59
	v_fmac_f32_e32 v73, v83, v101
	v_fmac_f32_e32 v70, v44, v60
	v_fmac_f32_e32 v73, v84, v102
	v_fmac_f32_e32 v70, v45, v61
	v_fmac_f32_e32 v73, v85, v103
	v_fmac_f32_e32 v70, v38, v54
	v_fmac_f32_e32 v73, v78, v96
	v_fmac_f32_e32 v70, v39, v55
	v_fmac_f32_e32 v73, v79, v97
	v_fmac_f32_e32 v70, v40, v56
	v_fmac_f32_e32 v73, v80, v98
	v_fmac_f32_e32 v70, v41, v57
	v_fmac_f32_e32 v73, v81, v99
	v_fmac_f32_e32 v70, v34, v50
	v_fmac_f32_e32 v73, v66, v92
	v_fmac_f32_e32 v70, v35, v51
	v_fmac_f32_e32 v73, v67, v93
	v_fmac_f32_e32 v70, v36, v52
	v_fmac_f32_e32 v73, v68, v94
	v_fmac_f32_e32 v70, v37, v53
	v_fmac_f32_e32 v73, v69, v95
	global_load_dwordx4 v[62:65], v107, s[94:95] offset:80
	global_load_dwordx4 v[78:81], v107, s[94:95] offset:64
	global_load_dwordx4 v[42:45], v107, s[94:95] offset:112
	global_load_dwordx4 v[50:53], v107, s[94:95] offset:96
	global_load_dwordx4 v[66:69], v107, s[94:95] offset:208
	global_load_dwordx4 v[82:85], v107, s[94:95] offset:192
	global_load_dwordx4 v[46:49], v107, s[94:95] offset:240
	global_load_dwordx4 v[54:57], v107, s[94:95] offset:224
	global_load_dwordx4 v[88:91], v107, s[94:95] offset:336
	global_load_dwordx4 v[92:95], v107, s[94:95] offset:320
	global_load_dwordx4 v[34:37], v107, s[94:95] offset:368
	global_load_dwordx4 v[58:61], v107, s[94:95] offset:352
	global_load_dwordx4 v[96:99], v107, s[94:95] offset:464
	global_load_dwordx4 v[100:103], v107, s[94:95] offset:448
	global_load_dwordx4 v[38:41], v107, s[94:95] offset:496
	global_load_dwordx4 v[108:111], v107, s[94:95] offset:480
	s_waitcnt vmcnt(10)
	v_fmac_f32_e32 v70, v78, v82
	v_fmac_f32_e32 v70, v79, v83
	s_waitcnt vmcnt(2)
	v_fmac_f32_e32 v73, v92, v100
	v_fmac_f32_e32 v70, v80, v84
	v_fmac_f32_e32 v73, v93, v101
	v_fmac_f32_e32 v70, v81, v85
	v_fmac_f32_e32 v73, v94, v102
	v_fmac_f32_e32 v70, v62, v66
	v_fmac_f32_e32 v73, v95, v103
	v_fmac_f32_e32 v70, v63, v67
	v_pk_mul_f32 v[62:63], v[64:65], v[68:69]
	v_fmac_f32_e32 v73, v88, v96
	v_add_f32_e32 v62, v70, v62
	v_fmac_f32_e32 v73, v89, v97
	v_add_f32_e32 v64, v62, v63
	v_pk_mul_f32 v[62:63], v[90:91], v[98:99]
	v_pk_mul_f32 v[50:51], v[50:51], v[54:55]
	v_add_f32_e32 v62, v73, v62
	v_add_f32_e32 v50, v64, v50
	v_add_f32_e32 v62, v62, v63
	v_add_f32_e32 v54, v50, v51
	s_waitcnt vmcnt(0)
	v_pk_mul_f32 v[50:51], v[58:59], v[108:109]
	v_pk_mul_f32 v[42:43], v[42:43], v[46:47]
	v_add_f32_e32 v50, v62, v50
	v_add_f32_e32 v55, v50, v51
	v_pk_mul_f32 v[50:51], v[52:53], v[56:57]
	v_pk_mul_f32 v[34:35], v[34:35], v[38:39]
	v_add_f32_e32 v50, v54, v50
	v_add_f32_e32 v52, v50, v51
	v_pk_mul_f32 v[50:51], v[60:61], v[110:111]
	v_add_f32_e32 v42, v52, v42
	v_add_f32_e32 v50, v55, v50
	v_add_f32_e32 v50, v50, v51
	v_add_f32_e32 v34, v50, v34
	v_add_f32_e32 v42, v42, v43
	v_add_f32_e32 v38, v34, v35
	v_pk_mul_f32 v[34:35], v[44:45], v[48:49]
	s_nop 0
	v_add_f32_e32 v34, v42, v34
	v_add_f32_e32 v39, v34, v35
	v_pk_mul_f32 v[34:35], v[36:37], v[40:41]
	v_cmp_ngt_f32_e32 vcc, s86, v39
	v_add_f32_e32 v34, v38, v34
	v_add_f32_e32 v34, v34, v35
	v_mul_f32_e32 v35, 0x3fb8aa3b, v39
	v_fma_f32 v36, v39, s62, -v35
	v_rndne_f32_e32 v37, v35
	v_fmac_f32_e32 v36, 0x32a5705f, v39
	v_sub_f32_e32 v35, v35, v37
	v_add_f32_e32 v35, v35, v36
	v_exp_f32_e32 v35, v35
	v_cvt_i32_f32_e32 v36, v37
	v_ldexp_f32 v35, v35, v36
	v_mul_f32_e32 v36, 0x3fb8aa3b, v34
	v_fma_f32 v37, v34, s62, -v36
	v_rndne_f32_e32 v38, v36
	v_fmac_f32_e32 v37, 0x32a5705f, v34
	v_sub_f32_e32 v36, v36, v38
	v_add_f32_e32 v36, v36, v37
	v_exp_f32_e32 v36, v36
	v_cvt_i32_f32_e32 v37, v38
	v_cndmask_b32_e32 v35, 0, v35, vcc
	v_cmp_nlt_f32_e32 vcc, s0, v39
	v_ldexp_f32 v36, v36, v37
	s_nop 0
	v_cndmask_b32_e32 v35, v148, v35, vcc
	v_cmp_ngt_f32_e32 vcc, s86, v34
	s_nop 1
	v_cndmask_b32_e32 v36, 0, v36, vcc
	v_cmp_nlt_f32_e32 vcc, s0, v34
	v_readlane_b32 s0, v204, 4
	v_readlane_b32 s1, v204, 5
	v_cndmask_b32_e32 v34, v148, v36, vcc
	v_div_scale_f32 v36, s[12:13], v72, v72, 1.0
	v_rcp_f32_e32 v37, v36
	v_sub_f32_e32 v70, v35, v34
	s_waitcnt lgkmcnt(0)
	v_pk_add_f32 v[34:35], v[86:87], v[70:71]
	v_fma_f32 v38, -v36, v37, 1.0
	v_fmac_f32_e32 v37, v38, v37
	v_div_scale_f32 v38, vcc, 1.0, v72, 1.0
	v_mul_f32_e32 v39, v38, v37
	v_fma_f32 v40, -v36, v39, v38
	v_fmac_f32_e32 v39, v40, v37
	v_fma_f32 v36, -v36, v39, v38
	v_div_fmas_f32 v36, v36, v37, v39
	v_div_fixup_f32 v38, v36, v72, 1.0
	v_div_scale_f32 v36, s[12:13], v35, v35, v34
	v_rcp_f32_e32 v37, v36
	s_nop 0
	v_fma_f32 v39, -v36, v37, 1.0
	v_fmac_f32_e32 v37, v39, v37
	v_div_scale_f32 v39, vcc, v34, v35, v34
	v_mul_f32_e32 v40, v39, v37
	v_fma_f32 v41, -v36, v40, v39
	v_fmac_f32_e32 v40, v41, v37
	v_fma_f32 v36, -v36, v40, v39
	v_div_fmas_f32 v36, v36, v37, v40
	v_div_fixup_f32 v40, v36, v35, v34
	v_pk_mul_f32 v[6:7], v[6:7], v[40:41] op_sel_hi:[1,0]
	v_pk_mul_f32 v[8:9], v[8:9], v[40:41] op_sel_hi:[1,0]
	v_pk_fma_f32 v[36:37], v[2:3], v[38:39], v[6:7] op_sel_hi:[1,0,1] neg_lo:[0,0,1] neg_hi:[0,0,1]
	v_pk_mul_f32 v[2:3], v[22:23], v[40:41] op_sel_hi:[1,0]
	v_pk_fma_f32 v[34:35], v[4:5], v[38:39], v[8:9] op_sel_hi:[1,0,1] neg_lo:[0,0,1] neg_hi:[0,0,1]
	v_pk_mul_f32 v[4:5], v[24:25], v[40:41] op_sel_hi:[1,0]
	v_pk_fma_f32 v[10:11], v[10:11], v[38:39], v[2:3] op_sel_hi:[1,0,1] neg_lo:[0,0,1] neg_hi:[0,0,1]
	v_pk_fma_f32 v[12:13], v[12:13], v[38:39], v[4:5] op_sel_hi:[1,0,1] neg_lo:[0,0,1] neg_hi:[0,0,1]
	v_mov_b32_e32 v4, v37
	v_mov_b32_e32 v5, v11
	v_mov_b32_e32 v2, v36
	v_mov_b32_e32 v3, v10
	v_pk_mul_f32 v[4:5], v[4:5], v[4:5]
	v_pk_mul_f32 v[6:7], v[28:29], v[40:41] op_sel_hi:[1,0]
	v_pk_fma_f32 v[2:3], v[2:3], v[2:3], v[4:5]
	v_mov_b32_e32 v4, v34
	v_mov_b32_e32 v5, v12
	v_pk_fma_f32 v[2:3], v[4:5], v[4:5], v[2:3]
	v_mov_b32_e32 v4, v35
	v_mov_b32_e32 v5, v13
	v_pk_fma_f32 v[2:3], v[4:5], v[4:5], v[2:3]
	v_pk_mul_f32 v[4:5], v[26:27], v[40:41] op_sel_hi:[1,0]
	v_pk_fma_f32 v[16:17], v[16:17], v[38:39], v[6:7] op_sel_hi:[1,0,1] neg_lo:[0,0,1] neg_hi:[0,0,1]
	v_pk_fma_f32 v[14:15], v[14:15], v[38:39], v[4:5] op_sel_hi:[1,0,1] neg_lo:[0,0,1] neg_hi:[0,0,1]
	v_pk_mul_f32 v[4:5], v[30:31], v[40:41] op_sel_hi:[1,0]
	v_pk_mul_f32 v[6:7], v[32:33], v[40:41] op_sel_hi:[1,0]
	v_pk_fma_f32 v[8:9], v[18:19], v[38:39], v[4:5] op_sel_hi:[1,0,1] neg_lo:[0,0,1] neg_hi:[0,0,1]
	v_mov_b32_e32 v19, v15
	v_mov_b32_e32 v18, v9
	v_pk_fma_f32 v[6:7], v[20:21], v[38:39], v[6:7] op_sel_hi:[1,0,1] neg_lo:[0,0,1] neg_hi:[0,0,1]
	v_mov_b32_e32 v4, v8
	v_mov_b32_e32 v5, v14
	v_pk_mul_f32 v[18:19], v[18:19], v[18:19]
	v_add_f32_e32 v2, v2, v3
	v_pk_fma_f32 v[4:5], v[4:5], v[4:5], v[18:19]
	v_mov_b32_e32 v18, v6
	v_mov_b32_e32 v19, v16
	v_pk_fma_f32 v[4:5], v[18:19], v[18:19], v[4:5]
	v_mov_b32_e32 v18, v7
	v_mov_b32_e32 v19, v17
	v_pk_fma_f32 v[4:5], v[18:19], v[18:19], v[4:5]
	v_lshlrev_b64 v[20:21], 10, v[76:77]
	v_add_f32_e32 v2, v5, v2
	v_add_f32_e32 v2, v4, v2
	ds_bpermute_b32 v3, v75, v2
	v_mov_b32_e32 v75, v107
	v_lshl_add_u64 v[20:21], s[0:1], 0, v[20:21]
	v_lshl_add_u64 v[20:21], v[20:21], 0, v[74:75]
	s_waitcnt lgkmcnt(0)
	v_add_f32_e32 v2, v2, v3
	ds_bpermute_b32 v1, v1, v2
	s_waitcnt lgkmcnt(0)
	v_add_f32_e32 v1, v2, v1
	v_fmamk_f32 v1, v1, 0x3c800000, v139
	v_cmp_gt_f32_e32 vcc, s56, v1
	v_mul_f32_e32 v2, 0x4b800000, v1
	s_nop 0
	v_cndmask_b32_e32 v1, v1, v2, vcc
	v_rsq_f32_e32 v1, v1
	s_nop 0
	v_mul_f32_e32 v2, 0x45800000, v1
	v_cndmask_b32_e32 v1, v1, v2, vcc
	global_load_dwordx4 v[2:5], v74, s[28:29]
	global_load_dwordx4 v[232:235], v74, s[28:29] offset:64
	global_load_dwordx4 v[236:239], v74, s[28:29] offset:128
	global_load_dwordx4 v[240:243], v74, s[28:29] offset:192
	v_mul_f32_e32 v18, v113, v1
	v_pk_mul_f32 v[22:23], v[36:37], v[18:19] op_sel_hi:[1,0]
	v_pk_mul_f32 v[24:25], v[34:35], v[18:19] op_sel_hi:[1,0]
	v_pk_mul_f32 v[12:13], v[12:13], v[18:19] op_sel_hi:[1,0]
	v_pk_mul_f32 v[10:11], v[10:11], v[18:19] op_sel_hi:[1,0]
	v_pk_mul_f32 v[6:7], v[6:7], v[18:19] op_sel_hi:[1,0]
	v_pk_mul_f32 v[8:9], v[8:9], v[18:19] op_sel_hi:[1,0]
	s_waitcnt vmcnt(0)
	v_pk_mul_f32 v[4:5], v[4:5], v[24:25]
	v_pk_mul_f32 v[2:3], v[2:3], v[22:23]
	v_pk_mul_f32 v[232:233], v[232:233], v[10:11]
	global_store_dwordx4 v[20:21], v[2:5], off
	v_pk_mul_f32 v[234:235], v[234:235], v[12:13]
	s_nop 0
	v_pk_mul_f32 v[10:11], v[16:17], v[18:19] op_sel_hi:[1,0]
	v_pk_mul_f32 v[12:13], v[14:15], v[18:19] op_sel_hi:[1,0]
	global_store_dwordx4 v[20:21], v[232:235], off offset:64
	v_pk_mul_f32 v[238:239], v[238:239], v[10:11]
	v_pk_mul_f32 v[240:241], v[240:241], v[8:9]
	v_pk_mul_f32 v[236:237], v[236:237], v[12:13]
	v_pk_mul_f32 v[242:243], v[242:243], v[6:7]
	global_store_dwordx4 v[20:21], v[236:239], off offset:128
	global_store_dwordx4 v[20:21], v[240:243], off offset:192

.LBB0_1184:
	s_cmp_gt_u32 s14, 3
	s_cselect_b64 s[68:69], -1, 0
	s_bitcmp1_b32 s14, 0
	s_cselect_b32 s14, 0x4800, 0
	v_or_b32_e32 v87, s14, v57
	v_add_u32_e32 v76, v87, v55
	ds_read_b128 v[60:63], v76
	ds_read_b128 v[64:67], v76 offset:64
	s_waitcnt vmcnt(1) lgkmcnt(1)
	v_mfma_f32_16x16x32_bf16 v[60:63], v[60:63], v[2:5], 0
	ds_read_b128 v[68:71], v76 offset:640
	ds_read_b128 v[72:75], v76 offset:4672
	s_waitcnt vmcnt(0) lgkmcnt(2)
	v_mfma_f32_16x16x32_bf16 v[60:63], v[64:67], v[6:9], v[60:63]
	ds_read_b128 v[64:67], v76 offset:576
	s_waitcnt lgkmcnt(0)
	v_mfma_f32_16x16x32_bf16 v[64:67], v[64:67], v[2:5], 0
	s_nop 4
	v_mul_f32_e32 v60, 0x3e38aa3b, v60
	v_mfma_f32_16x16x32_bf16 v[64:67], v[68:71], v[6:9], v[64:67]
	ds_read_b128 v[68:71], v76 offset:4608
	s_waitcnt lgkmcnt(0)
	v_mfma_f32_16x16x32_bf16 v[68:71], v[68:71], v[2:5], 0
	v_mfma_f32_16x16x32_bf16 v[68:71], v[72:75], v[6:9], v[68:71]
	ds_read_b128 v[72:75], v76 offset:5184
	ds_read_b128 v[76:79], v76 offset:5248
	s_waitcnt lgkmcnt(1)
	v_mfma_f32_16x16x32_bf16 v[72:75], v[72:75], v[2:5], 0
	s_waitcnt lgkmcnt(0)
	v_mfma_f32_16x16x32_bf16 v[72:75], v[76:79], v[6:9], v[72:75]
	v_add_u32_e32 v76, s12, v58
	v_add_u32_e32 v77, 0xfffffe3f, v76
	v_cmp_gt_u32_e32 vcc, s36, v77
	s_and_b64 vcc, s[68:69], vcc
	s_nop 0
	v_cndmask_b32_e32 v77, v60, v150, vcc
	v_mul_f32_e32 v60, 0x3e38aa3b, v61
	v_add_u32_e32 v61, 0xfffffe40, v76
	v_cmp_gt_u32_e32 vcc, s36, v61
	s_and_b64 vcc, s[68:69], vcc
	v_mul_f32_e32 v61, 0x3e38aa3b, v62
	v_add_u32_e32 v62, 0xfffffe41, v76
	v_cndmask_b32_e32 v78, v60, v150, vcc
	v_cmp_gt_u32_e32 vcc, s36, v62
	s_and_b64 vcc, s[68:69], vcc
	v_add_u32_e32 v62, 0xfffffe42, v76
	v_cndmask_b32_e32 v79, v61, v150, vcc
	v_cmp_gt_u32_e32 vcc, s36, v62
	v_mul_f32_e32 v61, 0x3e38aa3b, v63
	s_and_b64 vcc, s[68:69], vcc
	v_cndmask_b32_e32 v80, v61, v150, vcc
	v_add_u32_e32 v61, 0xfffffe43, v76
	v_cmp_gt_u32_e32 vcc, s36, v61
	v_mul_f32_e32 v62, 0x3e38aa3b, v64
	s_and_b64 vcc, s[68:69], vcc
	v_cndmask_b32_e32 v81, v62, v150, vcc
	v_add_u32_e32 v62, 0xfffffe44, v76
	v_cmp_gt_u32_e32 vcc, s36, v62
	v_mul_f32_e32 v61, 0x3e38aa3b, v65
	s_and_b64 vcc, s[68:69], vcc
	v_add_u32_e32 v62, 0xfffffe45, v76
	v_cndmask_b32_e32 v82, v61, v150, vcc
	v_cmp_gt_u32_e32 vcc, s36, v62
	v_mul_f32_e32 v61, 0x3e38aa3b, v66
	s_and_b64 vcc, s[68:69], vcc
	v_add_u32_e32 v62, 0xfffffe46, v76
	v_cndmask_b32_e32 v83, v61, v150, vcc
	v_cmp_gt_u32_e32 vcc, s36, v62
	v_mul_f32_e32 v61, 0x3e38aa3b, v67
	s_and_b64 vcc, s[68:69], vcc
	v_cndmask_b32_e32 v84, v61, v150, vcc
	v_add_u32_e32 v61, 0xfffffe5f, v76
	v_cmp_gt_u32_e32 vcc, s36, v61
	v_mul_f32_e32 v62, 0x3e38aa3b, v68
	s_and_b64 vcc, s[68:69], vcc
	v_cndmask_b32_e32 v85, v62, v150, vcc
	v_add_u32_e32 v62, 0xfffffe60, v76
	v_cmp_gt_u32_e32 vcc, s36, v62
	v_mul_f32_e32 v61, 0x3e38aa3b, v69
	s_and_b64 vcc, s[68:69], vcc
	v_add_u32_e32 v62, 0xfffffe61, v76
	v_cndmask_b32_e32 v88, v61, v150, vcc
	v_cmp_gt_u32_e32 vcc, s36, v62
	v_mul_f32_e32 v61, 0x3e38aa3b, v70
	s_and_b64 vcc, s[68:69], vcc
	v_add_u32_e32 v62, 0xfffffe62, v76
	v_cndmask_b32_e32 v89, v61, v150, vcc
	v_cmp_gt_u32_e32 vcc, s36, v62
	v_mul_f32_e32 v61, 0x3e38aa3b, v71
	s_and_b64 vcc, s[68:69], vcc
	v_cndmask_b32_e32 v90, v61, v150, vcc
	v_add_u32_e32 v61, 0xfffffe63, v76
	v_cmp_gt_u32_e32 vcc, s36, v61
	v_mul_f32_e32 v62, 0x3e38aa3b, v72
	s_and_b64 vcc, s[68:69], vcc
	v_cndmask_b32_e32 v91, v62, v150, vcc
	v_add_u32_e32 v62, 0xfffffe64, v76
	v_max3_f32 v60, v77, s88, v78
	v_cmp_gt_u32_e32 vcc, s36, v62
	v_max3_f32 v60, v60, v79, v80
	v_mul_f32_e32 v61, 0x3e38aa3b, v73
	s_and_b64 vcc, s[68:69], vcc
	v_add_u32_e32 v62, 0xfffffe65, v76
	v_max3_f32 v60, v60, v81, v82
	v_cndmask_b32_e32 v92, v61, v150, vcc
	v_cmp_gt_u32_e32 vcc, s36, v62
	v_max3_f32 v60, v60, v83, v84
	v_mul_f32_e32 v61, 0x3e38aa3b, v74
	s_and_b64 vcc, s[68:69], vcc
	v_add_u32_e32 v62, 0xfffffe66, v76
	v_max3_f32 v60, v60, v85, v88
	v_cndmask_b32_e32 v93, v61, v150, vcc
	v_cmp_gt_u32_e32 vcc, s36, v62
	v_max3_f32 v60, v60, v89, v90
	v_mul_f32_e32 v61, 0x3e38aa3b, v75
	s_and_b64 vcc, s[68:69], vcc
	v_max3_f32 v60, v60, v91, v92
	v_cndmask_b32_e32 v76, v61, v150, vcc
	v_max3_f32 v60, v60, v93, v76
	v_mov_b32_e32 v252, v60
	v_mov_b32_e32 v253, v60
	s_nop 1
	v_permlane16_swap_b32_e32 v252, v253
	s_andn2_b64 vcc, exec, s[60:61]
	s_waitcnt lgkmcnt(0)
	v_max_f32_e32 v60, v252, v253
	v_mov_b32_e32 v254, v60
	v_mov_b32_e32 v255, v60
	s_nop 1
	v_permlane32_swap_b32_e32 v254, v255
	s_waitcnt lgkmcnt(0)
	v_max3_f32 v60, v52, v254, v255
	v_sub_f32_e32 v61, v77, v60
	v_add_u32_e32 v77, v87, v56
	v_sub_f32_e32 v70, v88, v60
	v_sub_f32_e32 v71, v89, v60
	v_sub_f32_e32 v72, v90, v60
	v_sub_f32_e32 v73, v91, v60
	ds_read_b128 v[88:91], v77 offset:9216
	v_sub_f32_e32 v52, v52, v60
	v_sub_f32_e32 v62, v78, v60
	v_sub_f32_e32 v63, v79, v60
	v_sub_f32_e32 v64, v80, v60
	v_sub_f32_e32 v65, v81, v60
	v_sub_f32_e32 v66, v82, v60
	v_sub_f32_e32 v67, v83, v60
	v_sub_f32_e32 v68, v84, v60
	v_exp_f32_e32 v52, v52
	v_exp_f32_e32 v61, v61
	v_exp_f32_e32 v62, v62
	v_exp_f32_e32 v63, v63
	v_exp_f32_e32 v64, v64
	v_exp_f32_e32 v65, v65
	v_exp_f32_e32 v66, v66
	v_exp_f32_e32 v67, v67
	v_exp_f32_e32 v68, v68
	v_pk_mul_f32 v[28:29], v[28:29], v[52:53] op_sel_hi:[1,0]
	v_pk_mul_f32 v[26:27], v[26:27], v[52:53] op_sel_hi:[1,0]
	v_cvt_pk_bf16_f32 v78, v61, v62
	v_cvt_pk_bf16_f32 v79, v63, v64
	v_cvt_pk_bf16_f32 v80, v65, v66
	v_cvt_pk_bf16_f32 v81, v67, v68
	v_sub_f32_e32 v69, v85, v60
	v_sub_f32_e32 v74, v92, v60
	s_waitcnt lgkmcnt(0)
	v_mfma_f32_16x16x32_bf16 v[26:29], v[88:91], v[78:81], v[26:29]
	ds_read_b128 v[88:91], v77 offset:9280
	v_sub_f32_e32 v75, v93, v60
	v_sub_f32_e32 v76, v76, v60
	v_exp_f32_e32 v69, v69
	v_exp_f32_e32 v70, v70
	v_exp_f32_e32 v71, v71
	v_exp_f32_e32 v72, v72
	v_exp_f32_e32 v73, v73
	v_exp_f32_e32 v74, v74
	v_exp_f32_e32 v75, v75
	v_exp_f32_e32 v76, v76
	v_cvt_pk_bf16_f32 v82, v69, v70
	v_cvt_pk_bf16_f32 v83, v71, v72
	v_cvt_pk_bf16_f32 v84, v73, v74
	v_cvt_pk_bf16_f32 v85, v75, v76
	v_pk_mul_f32 v[32:33], v[32:33], v[52:53] op_sel_hi:[1,0]
	v_pk_mul_f32 v[30:31], v[30:31], v[52:53] op_sel_hi:[1,0]
	s_waitcnt lgkmcnt(0)
	v_mfma_f32_16x16x32_bf16 v[26:29], v[88:91], v[82:85], v[26:29]
	ds_read_b128 v[88:91], v77 offset:11520
	v_pk_mul_f32 v[36:37], v[36:37], v[52:53] op_sel_hi:[1,0]
	v_pk_mul_f32 v[34:35], v[34:35], v[52:53] op_sel_hi:[1,0]
	s_waitcnt lgkmcnt(0)
	v_mfma_f32_16x16x32_bf16 v[30:33], v[88:91], v[78:81], v[30:33]
	ds_read_b128 v[88:91], v77 offset:11584
	v_pk_mul_f32 v[40:41], v[40:41], v[52:53] op_sel_hi:[1,0]
	v_pk_mul_f32 v[38:39], v[38:39], v[52:53] op_sel_hi:[1,0]
	s_waitcnt lgkmcnt(0)
	v_mfma_f32_16x16x32_bf16 v[30:33], v[88:91], v[82:85], v[30:33]
	ds_read_b128 v[88:91], v77 offset:13824
	s_waitcnt lgkmcnt(0)
	v_mfma_f32_16x16x32_bf16 v[34:37], v[88:91], v[78:81], v[34:37]
	ds_read_b128 v[88:91], v77 offset:13888
	s_waitcnt lgkmcnt(0)
	v_mfma_f32_16x16x32_bf16 v[34:37], v[88:91], v[82:85], v[34:37]
	ds_read_b128 v[88:91], v77 offset:16128
	s_waitcnt lgkmcnt(0)
	v_mfma_f32_16x16x32_bf16 v[38:41], v[88:91], v[78:81], v[38:41]
	ds_read_b128 v[78:81], v77 offset:16192
	s_waitcnt lgkmcnt(0)
	v_mfma_f32_16x16x32_bf16 v[38:41], v[78:81], v[82:85], v[38:41]
	s_cbranch_vccnz .LBB0_1186
	s_bitcmp1_b32 s13, 0
	s_cselect_b32 s14, 0x4800, 0
	v_add_u32_e32 v77, s14, v48
	ds_write_b128 v77, v[14:17]
	ds_write_b128 v77, v[10:13] offset:16
	ds_write_b128 v77, v[22:25] offset:9216
	ds_write_b128 v77, v[18:21] offset:9232

.LBB0_1205:
	s_bitcmp1_b32 s12, 0
	s_cselect_b32 s12, 0x4800, 0
	v_or_b32_e32 v99, s12, v74
	v_add_u32_e32 v93, v99, v77
	ds_read_b128 v[62:65], v93
	ds_read_b128 v[66:69], v93 offset:576
	ds_read_b128 v[70:73], v93 offset:4608
	ds_read_b128 v[88:91], v93 offset:5184
	s_andn2_b64 vcc, exec, s[60:61]
	s_waitcnt vmcnt(1) lgkmcnt(3)
	v_mfma_f32_16x16x32_bf16 v[62:65], v[62:65], v[34:37], 0
	s_waitcnt lgkmcnt(2)
	v_mfma_f32_16x16x32_bf16 v[66:69], v[66:69], v[34:37], 0
	s_nop 5
	v_mul_f32_e32 v59, 0x3e8293ee, v62
	v_mul_f32_e32 v60, 0x3e8293ee, v63
	v_max3_f32 v59, v59, s88, v60
	s_waitcnt lgkmcnt(1)
	v_mfma_f32_16x16x32_bf16 v[70:73], v[70:73], v[34:37], 0
	v_mul_f32_e32 v60, 0x3e8293ee, v64
	v_mul_f32_e32 v81, 0x3e8293ee, v65
	v_max3_f32 v59, v59, v60, v81
	s_waitcnt lgkmcnt(0)
	v_mfma_f32_16x16x32_bf16 v[122:125], v[88:91], v[34:37], 0
	v_mul_f32_e32 v60, 0x3e8293ee, v66
	v_mul_f32_e32 v81, 0x3e8293ee, v67
	v_max3_f32 v59, v59, v60, v81
	v_mul_f32_e32 v60, 0x3e8293ee, v68
	v_mul_f32_e32 v81, 0x3e8293ee, v69
	v_max3_f32 v59, v59, v60, v81
	v_mul_f32_e32 v60, 0x3e8293ee, v70
	v_mul_f32_e32 v81, 0x3e8293ee, v71
	v_max3_f32 v59, v59, v60, v81
	v_mul_f32_e32 v60, 0x3e8293ee, v72
	v_mul_f32_e32 v81, 0x3e8293ee, v73
	v_max3_f32 v59, v59, v60, v81
	v_mul_f32_e32 v60, 0x3e8293ee, v122
	v_mul_f32_e32 v81, 0x3e8293ee, v123
	v_max3_f32 v59, v59, v60, v81
	v_mul_f32_e32 v60, 0x3e8293ee, v124
	v_mul_f32_e32 v81, 0x3e8293ee, v125
	v_max3_f32 v59, v59, v60, v81
	v_mov_b32_e32 v252, v59
	v_mov_b32_e32 v253, v59
	s_nop 1
	v_permlane16_swap_b32_e32 v252, v253
	s_waitcnt lgkmcnt(0)
	v_max_f32_e32 v59, v252, v253
	v_mov_b32_e32 v254, v59
	v_mov_b32_e32 v255, v59
	s_nop 1
	v_permlane32_swap_b32_e32 v254, v255
	s_waitcnt lgkmcnt(0)
	v_max3_f32 v81, v58, v254, v255
	v_fma_f32 v59, v62, s89, -v81
	v_exp_f32_e32 v115, v59
	v_fma_f32 v59, v63, s89, -v81
	v_exp_f32_e32 v116, v59
	v_fma_f32 v59, v64, s89, -v81
	v_exp_f32_e32 v117, v59
	v_fma_f32 v59, v65, s89, -v81
	v_exp_f32_e32 v118, v59
	v_fma_f32 v59, v66, s89, -v81
	v_exp_f32_e32 v119, v59
	v_fma_f32 v59, v67, s89, -v81
	v_exp_f32_e32 v120, v59
	v_fma_f32 v59, v68, s89, -v81
	v_exp_f32_e32 v96, v59
	v_fma_f32 v59, v69, s89, -v81
	v_exp_f32_e32 v110, v59
	v_fma_f32 v59, v70, s89, -v81
	v_exp_f32_e32 v94, v59
	v_fma_f32 v59, v71, s89, -v81
	ds_read_b128 v[62:65], v93 offset:64
	ds_read_b128 v[66:69], v93 offset:640
	v_exp_f32_e32 v108, v59
	v_fma_f32 v59, v72, s89, -v81
	v_exp_f32_e32 v92, v59
	v_fma_f32 v59, v73, s89, -v81
	v_exp_f32_e32 v104, v59
	v_fma_f32 v59, v122, s89, -v81
	v_exp_f32_e32 v90, v59
	v_fma_f32 v59, v123, s89, -v81
	ds_read_b128 v[70:73], v93 offset:4672
	v_exp_f32_e32 v102, v59
	v_fma_f32 v59, v124, s89, -v81
	v_exp_f32_e32 v88, v59
	v_fma_f32 v59, v125, s89, -v81
	ds_read_b128 v[122:125], v93 offset:5248
	s_waitcnt vmcnt(0) lgkmcnt(3)
	v_mfma_f32_16x16x32_bf16 v[62:65], v[62:65], v[42:45], 0
	v_sub_f32_e32 v58, v58, v81
	v_exp_f32_e32 v98, v58
	v_exp_f32_e32 v100, v59
	s_waitcnt lgkmcnt(2)
	v_mfma_f32_16x16x32_bf16 v[66:69], v[66:69], v[42:45], 0
	v_cvt_pk_bf16_f32 v58, v115, v116
	s_nop 1
	v_mul_f32_e32 v89, 0x3e8293ee, v62
	v_mul_f32_e32 v91, 0x3e8293ee, v63
	s_waitcnt lgkmcnt(1)
	v_mfma_f32_16x16x32_bf16 v[70:73], v[70:73], v[42:45], 0
	v_max3_f32 v89, v89, s88, v91
	v_mul_f32_e32 v91, 0x3e8293ee, v64
	v_mul_f32_e32 v93, 0x3e8293ee, v65
	s_waitcnt lgkmcnt(0)
	v_mfma_f32_16x16x32_bf16 v[128:131], v[122:125], v[42:45], 0
	v_max3_f32 v89, v89, v91, v93
	v_mul_f32_e32 v91, 0x3e8293ee, v66
	v_mul_f32_e32 v93, 0x3e8293ee, v67
	v_max3_f32 v89, v89, v91, v93
	v_mul_f32_e32 v91, 0x3e8293ee, v68
	v_mul_f32_e32 v93, 0x3e8293ee, v69
	v_max3_f32 v89, v89, v91, v93
	v_mul_f32_e32 v91, 0x3e8293ee, v70
	v_mul_f32_e32 v93, 0x3e8293ee, v71
	v_max3_f32 v89, v89, v91, v93
	v_mul_f32_e32 v91, 0x3e8293ee, v72
	v_mul_f32_e32 v93, 0x3e8293ee, v73
	v_max3_f32 v89, v89, v91, v93
	v_mul_f32_e32 v91, 0x3e8293ee, v128
	v_mul_f32_e32 v93, 0x3e8293ee, v129
	v_max3_f32 v89, v89, v91, v93
	v_mul_f32_e32 v91, 0x3e8293ee, v130
	v_mul_f32_e32 v93, 0x3e8293ee, v131
	v_max3_f32 v89, v89, v91, v93
	v_mov_b32_e32 v252, v89
	v_mov_b32_e32 v253, v89
	s_nop 1
	v_permlane16_swap_b32_e32 v252, v253
	v_pk_mul_f32 v[8:9], v[8:9], v[98:99] op_sel_hi:[1,0]
	v_pk_mul_f32 v[6:7], v[6:7], v[98:99] op_sel_hi:[1,0]
	v_pk_mul_f32 v[12:13], v[12:13], v[98:99] op_sel_hi:[1,0]
	v_pk_mul_f32 v[10:11], v[10:11], v[98:99] op_sel_hi:[1,0]
	s_waitcnt lgkmcnt(0)
	v_max_f32_e32 v89, v252, v253
	v_mov_b32_e32 v254, v89
	v_mov_b32_e32 v255, v89
	s_nop 1
	v_permlane32_swap_b32_e32 v254, v255
	v_pk_mul_f32 v[20:21], v[20:21], v[98:99] op_sel_hi:[1,0]
	v_pk_mul_f32 v[18:19], v[18:19], v[98:99] op_sel_hi:[1,0]
	v_cvt_pk_bf16_f32 v59, v117, v118
	v_cvt_pk_bf16_f32 v60, v119, v120
	s_waitcnt lgkmcnt(0)
	v_max3_f32 v121, v61, v254, v255
	v_fma_f32 v62, v62, s89, -v121
	v_exp_f32_e32 v122, v62
	v_fma_f32 v62, v63, s89, -v121
	v_exp_f32_e32 v123, v62
	v_fma_f32 v62, v64, s89, -v121
	v_exp_f32_e32 v124, v62
	v_fma_f32 v62, v65, s89, -v121
	v_exp_f32_e32 v125, v62
	v_fma_f32 v62, v66, s89, -v121
	v_exp_f32_e32 v126, v62
	v_fma_f32 v62, v67, s89, -v121
	v_exp_f32_e32 v127, v62
	v_fma_f32 v62, v68, s89, -v121
	v_exp_f32_e32 v97, v62
	v_fma_f32 v62, v69, s89, -v121
	v_exp_f32_e32 v111, v62
	v_fma_f32 v62, v70, s89, -v121
	v_exp_f32_e32 v95, v62
	v_fma_f32 v62, v71, s89, -v121
	v_exp_f32_e32 v109, v62
	v_fma_f32 v62, v72, s89, -v121
	v_exp_f32_e32 v93, v62
	v_fma_f32 v62, v73, s89, -v121
	v_exp_f32_e32 v105, v62
	v_fma_f32 v62, v128, s89, -v121
	v_exp_f32_e32 v91, v62
	v_fma_f32 v62, v129, s89, -v121
	v_exp_f32_e32 v103, v62
	v_fma_f32 v62, v130, s89, -v121
	v_exp_f32_e32 v89, v62
	v_fma_f32 v62, v131, s89, -v121
	v_exp_f32_e32 v101, v62
	v_pk_mul_f32 v[64:65], v[28:29], v[98:99] op_sel_hi:[1,0]
	v_pk_mul_f32 v[62:63], v[26:27], v[98:99] op_sel_hi:[1,0]
	v_add_u32_e32 v99, v99, v87
	ds_read_b128 v[128:131], v99 offset:9216
	v_sub_f32_e32 v61, v61, v121
	v_exp_f32_e32 v112, v61
	v_cvt_pk_bf16_f32 v61, v96, v110
	v_cvt_pk_bf16_f32 v70, v122, v123
	v_cvt_pk_bf16_f32 v71, v124, v125
	v_pk_mul_f32 v[4:5], v[4:5], v[112:113] op_sel_hi:[1,0]
	v_pk_mul_f32 v[2:3], v[2:3], v[112:113] op_sel_hi:[1,0]
	v_cvt_pk_bf16_f32 v72, v126, v127
	v_cvt_pk_bf16_f32 v73, v97, v111
	s_waitcnt lgkmcnt(0)
	v_mfma_f32_16x16x32_bf16 v[6:9], v[128:131], v[58:61], v[6:9]
	v_cvt_pk_bf16_f32 v26, v94, v108
	v_cvt_pk_bf16_f32 v27, v92, v104
	v_cvt_pk_bf16_f32 v28, v90, v102
	v_mfma_f32_16x16x32_bf16 v[2:5], v[128:131], v[70:73], v[2:5]
	ds_read_b128 v[128:131], v99 offset:9280
	v_cvt_pk_bf16_f32 v29, v88, v100
	v_pk_mul_f32 v[68:69], v[32:33], v[112:113] op_sel_hi:[1,0]
	v_pk_mul_f32 v[66:67], v[30:31], v[112:113] op_sel_hi:[1,0]
	v_cvt_pk_bf16_f32 v30, v95, v109
	v_cvt_pk_bf16_f32 v31, v93, v105
	v_cvt_pk_bf16_f32 v32, v91, v103
	v_cvt_pk_bf16_f32 v33, v89, v101
	s_waitcnt lgkmcnt(0)
	v_mfma_f32_16x16x32_bf16 v[6:9], v[128:131], v[26:29], v[6:9]
	v_mul_f32_e64 v16, v16, v112
	v_mul_f32_e64 v17, v17, v112
	v_pk_mul_f32 v[14:15], v[14:15], v[112:113] op_sel_hi:[1,0]
	v_pk_mul_f32 v[24:25], v[24:25], v[112:113] op_sel_hi:[1,0]
	v_mfma_f32_16x16x32_bf16 v[2:5], v[128:131], v[30:33], v[2:5]
	ds_read_b128 v[128:131], v99 offset:11520
	v_pk_mul_f32 v[22:23], v[22:23], v[112:113] op_sel_hi:[1,0]
	s_waitcnt lgkmcnt(0)
	v_mfma_f32_16x16x32_bf16 v[10:13], v[128:131], v[58:61], v[10:13]
	v_mfma_f32_16x16x32_bf16 v[14:17], v[128:131], v[70:73], v[14:17]
	ds_read_b128 v[128:131], v99 offset:11584
	s_waitcnt lgkmcnt(0)
	v_mfma_f32_16x16x32_bf16 v[10:13], v[128:131], v[26:29], v[10:13]
	v_mfma_f32_16x16x32_bf16 v[14:17], v[128:131], v[30:33], v[14:17]
	ds_read_b128 v[128:131], v99 offset:13824
	s_waitcnt lgkmcnt(0)
	v_mfma_f32_16x16x32_bf16 v[18:21], v[128:131], v[58:61], v[18:21]
	v_mfma_f32_16x16x32_bf16 v[22:25], v[128:131], v[70:73], v[22:25]
	ds_read_b128 v[128:131], v99 offset:13888
	s_waitcnt lgkmcnt(0)
	v_mfma_f32_16x16x32_bf16 v[18:21], v[128:131], v[26:29], v[18:21]
	v_mfma_f32_16x16x32_bf16 v[22:25], v[128:131], v[30:33], v[22:25]
	ds_read_b128 v[128:131], v99 offset:16128
	s_waitcnt lgkmcnt(0)
	v_mfma_f32_16x16x32_bf16 v[58:61], v[128:131], v[58:61], v[62:65]
	v_mfma_f32_16x16x32_bf16 v[62:65], v[128:131], v[70:73], v[66:69]
	s_nop 2
	ds_read_b128 v[66:69], v99 offset:16192
	s_waitcnt lgkmcnt(0)
	v_mfma_f32_16x16x32_bf16 v[26:29], v[66:69], v[26:29], v[58:61]
	v_mfma_f32_16x16x32_bf16 v[30:33], v[66:69], v[30:33], v[62:65]
	s_cbranch_vccnz .LBB0_1202
	s_bitcmp1_b32 s68, 0
	s_cselect_b32 s12, 0x4800, 0
	v_add_u32_e32 v58, s12, v80
	ds_write_b128 v58, v[46:49]
	ds_write_b128 v58, v[38:41] offset:16
	ds_write_b128 v58, v[54:57] offset:9216
	ds_write_b128 v58, v[50:53] offset:9232
	s_branch .LBB0_1202

.LBB0_1236:
	s_mov_b32 s4, 0xcccccccc
	s_mov_b32 s5, 0xcccccccc
	s_mov_b32 s12, 0xaaaaaaaa
	s_mov_b32 s13, 0xaaaaaaaa
	v_add_f32_dpp v232, v232, v232 row_ror:8 row_mask:0xf bank_mask:0x3
	v_add_f32_dpp v233, v233, v233 row_ror:8 row_mask:0xf bank_mask:0x3
	v_add_f32_dpp v234, v234, v234 row_ror:8 row_mask:0xf bank_mask:0x3
	v_add_f32_dpp v235, v235, v235 row_ror:8 row_mask:0xf bank_mask:0x3
	v_add_f32_dpp v236, v236, v236 row_ror:8 row_mask:0xf bank_mask:0x3
	v_add_f32_dpp v237, v237, v237 row_ror:8 row_mask:0xf bank_mask:0x3
	v_add_f32_dpp v238, v238, v238 row_ror:8 row_mask:0xf bank_mask:0x3
	v_add_f32_dpp v239, v239, v239 row_ror:8 row_mask:0xf bank_mask:0x3
	v_add_f32_dpp v232, v240, v240 row_ror:8 row_mask:0xf bank_mask:0xc
	v_add_f32_dpp v233, v241, v241 row_ror:8 row_mask:0xf bank_mask:0xc
	v_add_f32_dpp v234, v242, v242 row_ror:8 row_mask:0xf bank_mask:0xc
	v_add_f32_dpp v235, v243, v243 row_ror:8 row_mask:0xf bank_mask:0xc
	v_add_f32_dpp v236, v244, v244 row_ror:8 row_mask:0xf bank_mask:0xc
	v_add_f32_dpp v237, v245, v245 row_ror:8 row_mask:0xf bank_mask:0xc
	v_add_f32_dpp v238, v246, v246 row_ror:8 row_mask:0xf bank_mask:0xc
	v_add_f32_dpp v239, v247, v247 row_ror:8 row_mask:0xf bank_mask:0xc
	v_add_f32_dpp v232, v232, v232 row_shl:4 row_mask:0xf bank_mask:0x5
	v_add_f32_dpp v233, v233, v233 row_shl:4 row_mask:0xf bank_mask:0x5
	v_add_f32_dpp v234, v234, v234 row_shl:4 row_mask:0xf bank_mask:0x5
	v_add_f32_dpp v235, v235, v235 row_shl:4 row_mask:0xf bank_mask:0x5
	v_add_f32_dpp v232, v236, v236 row_shr:4 row_mask:0xf bank_mask:0xa
	v_add_f32_dpp v233, v237, v237 row_shr:4 row_mask:0xf bank_mask:0xa
	v_add_f32_dpp v234, v238, v238 row_shr:4 row_mask:0xf bank_mask:0xa
	v_add_f32_dpp v235, v239, v239 row_shr:4 row_mask:0xf bank_mask:0xa
	v_add_f32_dpp v240, v232, v232 quad_perm:[2,3,0,1] row_mask:0xf bank_mask:0xf
	v_add_f32_dpp v241, v233, v233 quad_perm:[2,3,0,1] row_mask:0xf bank_mask:0xf
	v_add_f32_dpp v242, v234, v234 quad_perm:[2,3,0,1] row_mask:0xf bank_mask:0xf
	v_add_f32_dpp v243, v235, v235 quad_perm:[2,3,0,1] row_mask:0xf bank_mask:0xf
	v_cndmask_b32_e64 v236, v240, v242, s[4:5]
	v_cndmask_b32_e64 v237, v241, v243, s[4:5]
	s_nop 0
	v_add_f32_dpp v238, v236, v236 quad_perm:[1,0,3,2] row_mask:0xf bank_mask:0xf
	v_add_f32_dpp v239, v237, v237 quad_perm:[1,0,3,2] row_mask:0xf bank_mask:0xf
	v_cndmask_b32_e64 v249, v238, v239, s[12:13]
	s_sub_i32 s2, s10, 1
	v_lshl_or_b32 v250, s2, 4, v87
	v_xad_u32 v251, v250, -1, s18
	s_nop 0
	v_cndmask_b32_e64 v250, v251, v250, s[16:17]
	v_ashrrev_i32_e32 v251, 31, v250
	v_lshlrev_b64 v[250:251], 10, v[250:251]
	v_lshl_add_u64 v[250:251], v[98:99], 0, v[250:251]
	global_store_dword v[250:251], v249, off
	s_setprio 0
	v_readlane_b32 s0, v206, 0
	v_readlane_b32 s1, v206, 1
	s_and_b64 vcc, exec, s[0:1]
	s_cbranch_vccnz .LBB0_1240

.LBB0_1251:
	ds_read_b128 v[156:159], v90 offset:0
	ds_read_b128 v[160:163], v90 offset:256
	ds_read_b128 v[168:171], v90 offset:768
	ds_read_b32 v176, v103 offset:1280
	ds_read_b128 v[164:167], v90 offset:512
	ds_read_b128 v[172:175], v90 offset:1024
	ds_read_b128 v[180:183], v90 offset:1536
	ds_read_b128 v[184:187], v90 offset:1792
	ds_read_b128 v[192:195], v90 offset:2304
	ds_read_b32 v178, v103 offset:2816
	ds_read_b128 v[188:191], v90 offset:2048
	ds_read_b128 v[196:199], v90 offset:2560
	ds_read_b128 v[52:55], v90 offset:3072
	ds_read_b128 v[56:59], v90 offset:3328
	ds_read_b128 v[64:67], v90 offset:3840
	ds_read_b32 v200, v103 offset:4352
	ds_read_b128 v[60:63], v90 offset:3584
	ds_read_b128 v[68:71], v90 offset:4096
	s_cmp_eq_u32 s7, 0
	s_cbranch_scc1 .Lrw_skip_pend_e
	s_mov_b32 s4, 0xcccccccc
	s_mov_b32 s5, 0xcccccccc
	s_mov_b32 s12, 0xaaaaaaaa
	s_mov_b32 s13, 0xaaaaaaaa
	v_add_f32_dpp v232, v232, v232 row_ror:8 row_mask:0xf bank_mask:0x3
	v_add_f32_dpp v233, v233, v233 row_ror:8 row_mask:0xf bank_mask:0x3
	v_add_f32_dpp v234, v234, v234 row_ror:8 row_mask:0xf bank_mask:0x3
	v_add_f32_dpp v235, v235, v235 row_ror:8 row_mask:0xf bank_mask:0x3
	v_add_f32_dpp v236, v236, v236 row_ror:8 row_mask:0xf bank_mask:0x3
	v_add_f32_dpp v237, v237, v237 row_ror:8 row_mask:0xf bank_mask:0x3
	v_add_f32_dpp v238, v238, v238 row_ror:8 row_mask:0xf bank_mask:0x3
	v_add_f32_dpp v239, v239, v239 row_ror:8 row_mask:0xf bank_mask:0x3
	v_add_f32_dpp v232, v240, v240 row_ror:8 row_mask:0xf bank_mask:0xc
	v_add_f32_dpp v233, v241, v241 row_ror:8 row_mask:0xf bank_mask:0xc
	v_add_f32_dpp v234, v242, v242 row_ror:8 row_mask:0xf bank_mask:0xc
	v_add_f32_dpp v235, v243, v243 row_ror:8 row_mask:0xf bank_mask:0xc
	v_add_f32_dpp v236, v244, v244 row_ror:8 row_mask:0xf bank_mask:0xc
	v_add_f32_dpp v237, v245, v245 row_ror:8 row_mask:0xf bank_mask:0xc
	v_add_f32_dpp v238, v246, v246 row_ror:8 row_mask:0xf bank_mask:0xc
	v_add_f32_dpp v239, v247, v247 row_ror:8 row_mask:0xf bank_mask:0xc
	v_add_f32_dpp v232, v232, v232 row_shl:4 row_mask:0xf bank_mask:0x5
	v_add_f32_dpp v233, v233, v233 row_shl:4 row_mask:0xf bank_mask:0x5
	v_add_f32_dpp v234, v234, v234 row_shl:4 row_mask:0xf bank_mask:0x5
	v_add_f32_dpp v235, v235, v235 row_shl:4 row_mask:0xf bank_mask:0x5
	v_add_f32_dpp v232, v236, v236 row_shr:4 row_mask:0xf bank_mask:0xa
	v_add_f32_dpp v233, v237, v237 row_shr:4 row_mask:0xf bank_mask:0xa
	v_add_f32_dpp v234, v238, v238 row_shr:4 row_mask:0xf bank_mask:0xa
	v_add_f32_dpp v235, v239, v239 row_shr:4 row_mask:0xf bank_mask:0xa
	v_add_f32_dpp v240, v232, v232 quad_perm:[2,3,0,1] row_mask:0xf bank_mask:0xf
	v_add_f32_dpp v241, v233, v233 quad_perm:[2,3,0,1] row_mask:0xf bank_mask:0xf
	v_add_f32_dpp v242, v234, v234 quad_perm:[2,3,0,1] row_mask:0xf bank_mask:0xf
	v_add_f32_dpp v243, v235, v235 quad_perm:[2,3,0,1] row_mask:0xf bank_mask:0xf
	v_cndmask_b32_e64 v236, v240, v242, s[4:5]
	v_cndmask_b32_e64 v237, v241, v243, s[4:5]
	s_nop 0
	v_add_f32_dpp v238, v236, v236 quad_perm:[1,0,3,2] row_mask:0xf bank_mask:0xf
	v_add_f32_dpp v239, v237, v237 quad_perm:[1,0,3,2] row_mask:0xf bank_mask:0xf
	v_cndmask_b32_e64 v249, v238, v239, s[12:13]
	s_sub_i32 s2, s7, 1
	v_lshl_or_b32 v250, s2, 4, v87
	v_xad_u32 v251, v250, -1, s18
	s_nop 0
	v_cndmask_b32_e64 v250, v251, v250, s[16:17]
	v_ashrrev_i32_e32 v251, 31, v250
	v_lshlrev_b64 v[250:251], 10, v[250:251]
	v_lshl_add_u64 v[250:251], v[98:99], 0, v[250:251]
	global_store_dword v[250:251], v249, off
.Lrw_skip_pend_e:
	s_waitcnt lgkmcnt(12)
	v_pk_mul_f32 v[72:73], v[44:45], v[158:159]
	v_pk_mul_f32 v[74:75], v[42:43], v[160:161]
	v_pk_fma_f32 v[72:73], v[42:43], v[156:157], v[72:73]
	v_pk_mul_f32 v[76:77], v[44:45], v[162:163]
	v_add_f32_e32 v78, v72, v73
	v_pk_fma_f32 v[74:75], v[176:177], v[168:169], v[74:75] op_sel_hi:[0,1,1]
	v_pk_fma_f32 v[76:77], v[176:177], v[170:171], v[76:77] op_sel_hi:[0,1,1]
	v_add_f32_dpp v78, v78, v78 quad_perm:[1,0,3,2] row_mask:0xf bank_mask:0xf bound_ctrl:1
	ds_read_b128 v[210:213], v90 offset:4608
	ds_read_b128 v[214:217], v90 offset:4864
	v_add_f32_dpp v78, v78, v78 quad_perm:[2,3,0,1] row_mask:0xf bank_mask:0xf bound_ctrl:1
	ds_read_b128 v[222:225], v90 offset:5376
	ds_read_b32 v230, v103 offset:5888
	v_add_f32_dpp v78, v78, v78 row_half_mirror row_mask:0xf bank_mask:0xf bound_ctrl:1
	ds_read_b128 v[218:221], v90 offset:5120
	ds_read_b128 v[226:229], v90 offset:5632
	v_add_f32_dpp v78, v78, v78 row_mirror row_mask:0xf bank_mask:0xf bound_ctrl:1
	v_pk_fma_f32 v[44:45], v[166:167], v[78:79], v[76:77] op_sel_hi:[1,0,1]
	v_pk_fma_f32 v[42:43], v[164:165], v[78:79], v[74:75] op_sel_hi:[1,0,1]
	s_waitcnt lgkmcnt(12)
	v_pk_mul_f32 v[72:73], v[44:45], v[182:183]
	v_pk_mul_f32 v[80:81], v[44:45], v[174:175]
	v_pk_fma_f32 v[72:73], v[42:43], v[180:181], v[72:73]
	v_pk_fma_f32 v[80:81], v[42:43], v[172:173], v[80:81]
	v_add_f32_e32 v78, v72, v73
	v_add_f32_e32 v232, v80, v81
	v_pk_mul_f32 v[74:75], v[42:43], v[184:185]
	v_add_f32_dpp v78, v78, v78 quad_perm:[1,0,3,2] row_mask:0xf bank_mask:0xf bound_ctrl:1
	v_pk_mul_f32 v[76:77], v[44:45], v[186:187]
	v_pk_fma_f32 v[74:75], v[178:179], v[192:193], v[74:75] op_sel_hi:[0,1,1]
	v_add_f32_dpp v78, v78, v78 quad_perm:[2,3,0,1] row_mask:0xf bank_mask:0xf bound_ctrl:1
	v_pk_fma_f32 v[76:77], v[178:179], v[194:195], v[76:77] op_sel_hi:[0,1,1]
	ds_read_b128 v[156:159], v90 offset:6144
	v_add_f32_dpp v78, v78, v78 row_half_mirror row_mask:0xf bank_mask:0xf bound_ctrl:1
	ds_read_b128 v[160:163], v90 offset:6400
	ds_read_b128 v[168:171], v90 offset:6912
	v_add_f32_dpp v78, v78, v78 row_mirror row_mask:0xf bank_mask:0xf bound_ctrl:1
	v_pk_fma_f32 v[44:45], v[190:191], v[78:79], v[76:77] op_sel_hi:[1,0,1]
	v_pk_fma_f32 v[42:43], v[188:189], v[78:79], v[74:75] op_sel_hi:[1,0,1]
	ds_read_b32 v176, v103 offset:7424
	ds_read_b128 v[164:167], v90 offset:6656
	ds_read_b128 v[172:175], v90 offset:7168
	s_waitcnt lgkmcnt(12)
	v_pk_mul_f32 v[72:73], v[44:45], v[54:55]
	v_pk_mul_f32 v[80:81], v[44:45], v[198:199]
	v_pk_fma_f32 v[72:73], v[42:43], v[52:53], v[72:73]
	v_pk_fma_f32 v[80:81], v[42:43], v[196:197], v[80:81]
	v_add_f32_e32 v78, v72, v73
	v_add_f32_e32 v233, v80, v81
	v_pk_mul_f32 v[74:75], v[42:43], v[56:57]
	v_add_f32_dpp v78, v78, v78 quad_perm:[1,0,3,2] row_mask:0xf bank_mask:0xf bound_ctrl:1
	v_pk_mul_f32 v[76:77], v[44:45], v[58:59]
	v_pk_fma_f32 v[74:75], v[200:201], v[64:65], v[74:75] op_sel_hi:[0,1,1]
	v_add_f32_dpp v78, v78, v78 quad_perm:[2,3,0,1] row_mask:0xf bank_mask:0xf bound_ctrl:1
	v_pk_fma_f32 v[76:77], v[200:201], v[66:67], v[76:77] op_sel_hi:[0,1,1]
	ds_read_b128 v[180:183], v90 offset:7680
	v_add_f32_dpp v78, v78, v78 row_half_mirror row_mask:0xf bank_mask:0xf bound_ctrl:1
	ds_read_b128 v[184:187], v90 offset:7936
	ds_read_b128 v[192:195], v90 offset:8448
	v_add_f32_dpp v78, v78, v78 row_mirror row_mask:0xf bank_mask:0xf bound_ctrl:1
	v_pk_fma_f32 v[44:45], v[62:63], v[78:79], v[76:77] op_sel_hi:[1,0,1]
	v_pk_fma_f32 v[42:43], v[60:61], v[78:79], v[74:75] op_sel_hi:[1,0,1]
	ds_read_b32 v178, v103 offset:8960
	ds_read_b128 v[188:191], v90 offset:8192
	ds_read_b128 v[196:199], v90 offset:8704
	s_waitcnt lgkmcnt(12)
	v_pk_mul_f32 v[72:73], v[44:45], v[212:213]
	v_pk_mul_f32 v[80:81], v[44:45], v[70:71]
	v_pk_fma_f32 v[72:73], v[42:43], v[210:211], v[72:73]
	v_pk_fma_f32 v[80:81], v[42:43], v[68:69], v[80:81]
	v_add_f32_e32 v78, v72, v73
	v_add_f32_e32 v234, v80, v81
	v_pk_mul_f32 v[74:75], v[42:43], v[214:215]
	v_add_f32_dpp v78, v78, v78 quad_perm:[1,0,3,2] row_mask:0xf bank_mask:0xf bound_ctrl:1
	v_pk_mul_f32 v[76:77], v[44:45], v[216:217]
	v_pk_fma_f32 v[74:75], v[230:231], v[222:223], v[74:75] op_sel_hi:[0,1,1]
	v_add_f32_dpp v78, v78, v78 quad_perm:[2,3,0,1] row_mask:0xf bank_mask:0xf bound_ctrl:1
	v_pk_fma_f32 v[76:77], v[230:231], v[224:225], v[76:77] op_sel_hi:[0,1,1]
	ds_read_b128 v[52:55], v90 offset:9216
	v_add_f32_dpp v78, v78, v78 row_half_mirror row_mask:0xf bank_mask:0xf bound_ctrl:1
	ds_read_b128 v[56:59], v90 offset:9472
	ds_read_b128 v[64:67], v90 offset:9984
	v_add_f32_dpp v78, v78, v78 row_mirror row_mask:0xf bank_mask:0xf bound_ctrl:1
	v_pk_fma_f32 v[44:45], v[220:221], v[78:79], v[76:77] op_sel_hi:[1,0,1]
	v_pk_fma_f32 v[42:43], v[218:219], v[78:79], v[74:75] op_sel_hi:[1,0,1]
	ds_read_b32 v200, v103 offset:10496
	ds_read_b128 v[60:63], v90 offset:9728
	ds_read_b128 v[68:71], v90 offset:10240
	s_waitcnt lgkmcnt(12)
	v_pk_mul_f32 v[72:73], v[44:45], v[158:159]
	v_pk_mul_f32 v[80:81], v[44:45], v[228:229]
	v_pk_fma_f32 v[72:73], v[42:43], v[156:157], v[72:73]
	v_pk_fma_f32 v[80:81], v[42:43], v[226:227], v[80:81]
	v_add_f32_e32 v78, v72, v73
	v_add_f32_e32 v235, v80, v81
	v_pk_mul_f32 v[74:75], v[42:43], v[160:161]
	v_add_f32_dpp v78, v78, v78 quad_perm:[1,0,3,2] row_mask:0xf bank_mask:0xf bound_ctrl:1
	v_pk_mul_f32 v[76:77], v[44:45], v[162:163]
	v_pk_fma_f32 v[74:75], v[176:177], v[168:169], v[74:75] op_sel_hi:[0,1,1]
	v_add_f32_dpp v78, v78, v78 quad_perm:[2,3,0,1] row_mask:0xf bank_mask:0xf bound_ctrl:1
	v_pk_fma_f32 v[76:77], v[176:177], v[170:171], v[76:77] op_sel_hi:[0,1,1]
	ds_read_b128 v[210:213], v90 offset:10752
	v_add_f32_dpp v78, v78, v78 row_half_mirror row_mask:0xf bank_mask:0xf bound_ctrl:1
	ds_read_b128 v[214:217], v90 offset:11008
	ds_read_b128 v[222:225], v90 offset:11520
	v_add_f32_dpp v78, v78, v78 row_mirror row_mask:0xf bank_mask:0xf bound_ctrl:1
	v_pk_fma_f32 v[44:45], v[166:167], v[78:79], v[76:77] op_sel_hi:[1,0,1]
	v_pk_fma_f32 v[42:43], v[164:165], v[78:79], v[74:75] op_sel_hi:[1,0,1]
	ds_read_b32 v230, v103 offset:12032
	ds_read_b128 v[218:221], v90 offset:11264
	ds_read_b128 v[226:229], v90 offset:11776
	s_waitcnt lgkmcnt(12)
	v_pk_mul_f32 v[72:73], v[44:45], v[182:183]
	v_pk_mul_f32 v[80:81], v[44:45], v[174:175]
	v_pk_fma_f32 v[72:73], v[42:43], v[180:181], v[72:73]
	v_pk_fma_f32 v[80:81], v[42:43], v[172:173], v[80:81]
	v_add_f32_e32 v78, v72, v73
	v_add_f32_e32 v236, v80, v81
	v_pk_mul_f32 v[74:75], v[42:43], v[184:185]
	v_add_f32_dpp v78, v78, v78 quad_perm:[1,0,3,2] row_mask:0xf bank_mask:0xf bound_ctrl:1
	v_pk_mul_f32 v[76:77], v[44:45], v[186:187]
	v_pk_fma_f32 v[74:75], v[178:179], v[192:193], v[74:75] op_sel_hi:[0,1,1]
	v_add_f32_dpp v78, v78, v78 quad_perm:[2,3,0,1] row_mask:0xf bank_mask:0xf bound_ctrl:1
	v_pk_fma_f32 v[76:77], v[178:179], v[194:195], v[76:77] op_sel_hi:[0,1,1]
	ds_read_b128 v[156:159], v90 offset:12288
	v_add_f32_dpp v78, v78, v78 row_half_mirror row_mask:0xf bank_mask:0xf bound_ctrl:1
	ds_read_b128 v[160:163], v90 offset:12544
	ds_read_b128 v[168:171], v90 offset:13056
	v_add_f32_dpp v78, v78, v78 row_mirror row_mask:0xf bank_mask:0xf bound_ctrl:1
	v_pk_fma_f32 v[44:45], v[190:191], v[78:79], v[76:77] op_sel_hi:[1,0,1]
	v_pk_fma_f32 v[42:43], v[188:189], v[78:79], v[74:75] op_sel_hi:[1,0,1]
	ds_read_b32 v176, v103 offset:13568
	ds_read_b128 v[164:167], v90 offset:12800
	ds_read_b128 v[172:175], v90 offset:13312
	s_waitcnt lgkmcnt(12)
	v_pk_mul_f32 v[72:73], v[44:45], v[54:55]
	v_pk_mul_f32 v[80:81], v[44:45], v[198:199]
	v_pk_fma_f32 v[72:73], v[42:43], v[52:53], v[72:73]
	v_pk_fma_f32 v[80:81], v[42:43], v[196:197], v[80:81]
	v_add_f32_e32 v78, v72, v73
	v_add_f32_e32 v237, v80, v81
	v_pk_mul_f32 v[74:75], v[42:43], v[56:57]
	v_add_f32_dpp v78, v78, v78 quad_perm:[1,0,3,2] row_mask:0xf bank_mask:0xf bound_ctrl:1
	v_pk_mul_f32 v[76:77], v[44:45], v[58:59]
	v_pk_fma_f32 v[74:75], v[200:201], v[64:65], v[74:75] op_sel_hi:[0,1,1]
	v_add_f32_dpp v78, v78, v78 quad_perm:[2,3,0,1] row_mask:0xf bank_mask:0xf bound_ctrl:1
	v_pk_fma_f32 v[76:77], v[200:201], v[66:67], v[76:77] op_sel_hi:[0,1,1]
	ds_read_b128 v[180:183], v90 offset:13824
	v_add_f32_dpp v78, v78, v78 row_half_mirror row_mask:0xf bank_mask:0xf bound_ctrl:1
	ds_read_b128 v[184:187], v90 offset:14080
	ds_read_b128 v[192:195], v90 offset:14592
	v_add_f32_dpp v78, v78, v78 row_mirror row_mask:0xf bank_mask:0xf bound_ctrl:1
	v_pk_fma_f32 v[44:45], v[62:63], v[78:79], v[76:77] op_sel_hi:[1,0,1]
	v_pk_fma_f32 v[42:43], v[60:61], v[78:79], v[74:75] op_sel_hi:[1,0,1]
	ds_read_b32 v178, v103 offset:15104
	ds_read_b128 v[188:191], v90 offset:14336
	ds_read_b128 v[196:199], v90 offset:14848
	s_waitcnt lgkmcnt(12)
	v_pk_mul_f32 v[72:73], v[44:45], v[212:213]
	v_pk_mul_f32 v[80:81], v[44:45], v[70:71]
	v_pk_fma_f32 v[72:73], v[42:43], v[210:211], v[72:73]
	v_pk_fma_f32 v[80:81], v[42:43], v[68:69], v[80:81]
	v_add_f32_e32 v78, v72, v73
	v_add_f32_e32 v238, v80, v81
	v_pk_mul_f32 v[74:75], v[42:43], v[214:215]
	v_add_f32_dpp v78, v78, v78 quad_perm:[1,0,3,2] row_mask:0xf bank_mask:0xf bound_ctrl:1
	v_pk_mul_f32 v[76:77], v[44:45], v[216:217]
	v_pk_fma_f32 v[74:75], v[230:231], v[222:223], v[74:75] op_sel_hi:[0,1,1]
	v_add_f32_dpp v78, v78, v78 quad_perm:[2,3,0,1] row_mask:0xf bank_mask:0xf bound_ctrl:1
	v_pk_fma_f32 v[76:77], v[230:231], v[224:225], v[76:77] op_sel_hi:[0,1,1]
	ds_read_b128 v[52:55], v90 offset:15360
	v_add_f32_dpp v78, v78, v78 row_half_mirror row_mask:0xf bank_mask:0xf bound_ctrl:1
	ds_read_b128 v[56:59], v90 offset:15616
	ds_read_b128 v[64:67], v90 offset:16128
	v_add_f32_dpp v78, v78, v78 row_mirror row_mask:0xf bank_mask:0xf bound_ctrl:1
	v_pk_fma_f32 v[44:45], v[220:221], v[78:79], v[76:77] op_sel_hi:[1,0,1]
	v_pk_fma_f32 v[42:43], v[218:219], v[78:79], v[74:75] op_sel_hi:[1,0,1]
	ds_read_b32 v200, v103 offset:16640
	ds_read_b128 v[60:63], v90 offset:15872
	ds_read_b128 v[68:71], v90 offset:16384
	s_waitcnt lgkmcnt(12)
	v_pk_mul_f32 v[72:73], v[44:45], v[158:159]
	v_pk_mul_f32 v[80:81], v[44:45], v[228:229]
	v_pk_fma_f32 v[72:73], v[42:43], v[156:157], v[72:73]
	v_pk_fma_f32 v[80:81], v[42:43], v[226:227], v[80:81]
	v_add_f32_e32 v78, v72, v73
	v_add_f32_e32 v239, v80, v81
	v_pk_mul_f32 v[74:75], v[42:43], v[160:161]
	v_add_f32_dpp v78, v78, v78 quad_perm:[1,0,3,2] row_mask:0xf bank_mask:0xf bound_ctrl:1
	v_pk_mul_f32 v[76:77], v[44:45], v[162:163]
	v_pk_fma_f32 v[74:75], v[176:177], v[168:169], v[74:75] op_sel_hi:[0,1,1]
	v_add_f32_dpp v78, v78, v78 quad_perm:[2,3,0,1] row_mask:0xf bank_mask:0xf bound_ctrl:1
	v_pk_fma_f32 v[76:77], v[176:177], v[170:171], v[76:77] op_sel_hi:[0,1,1]
	ds_read_b128 v[210:213], v90 offset:16896
	v_add_f32_dpp v78, v78, v78 row_half_mirror row_mask:0xf bank_mask:0xf bound_ctrl:1
	ds_read_b128 v[214:217], v90 offset:17152
	ds_read_b128 v[222:225], v90 offset:17664
	v_add_f32_dpp v78, v78, v78 row_mirror row_mask:0xf bank_mask:0xf bound_ctrl:1
	v_pk_fma_f32 v[44:45], v[166:167], v[78:79], v[76:77] op_sel_hi:[1,0,1]
	v_pk_fma_f32 v[42:43], v[164:165], v[78:79], v[74:75] op_sel_hi:[1,0,1]
	ds_read_b32 v230, v103 offset:18176
	ds_read_b128 v[218:221], v90 offset:17408
	ds_read_b128 v[226:229], v90 offset:17920
	s_waitcnt lgkmcnt(12)
	v_pk_mul_f32 v[72:73], v[44:45], v[182:183]
	v_pk_mul_f32 v[80:81], v[44:45], v[174:175]
	v_pk_fma_f32 v[72:73], v[42:43], v[180:181], v[72:73]
	v_pk_fma_f32 v[80:81], v[42:43], v[172:173], v[80:81]
	v_add_f32_e32 v78, v72, v73
	v_add_f32_e32 v240, v80, v81
	v_pk_mul_f32 v[74:75], v[42:43], v[184:185]
	v_add_f32_dpp v78, v78, v78 quad_perm:[1,0,3,2] row_mask:0xf bank_mask:0xf bound_ctrl:1
	v_pk_mul_f32 v[76:77], v[44:45], v[186:187]
	v_pk_fma_f32 v[74:75], v[178:179], v[192:193], v[74:75] op_sel_hi:[0,1,1]
	v_add_f32_dpp v78, v78, v78 quad_perm:[2,3,0,1] row_mask:0xf bank_mask:0xf bound_ctrl:1
	v_pk_fma_f32 v[76:77], v[178:179], v[194:195], v[76:77] op_sel_hi:[0,1,1]
	ds_read_b128 v[156:159], v90 offset:18432
	v_add_f32_dpp v78, v78, v78 row_half_mirror row_mask:0xf bank_mask:0xf bound_ctrl:1
	ds_read_b128 v[160:163], v90 offset:18688
	ds_read_b128 v[168:171], v90 offset:19200
	v_add_f32_dpp v78, v78, v78 row_mirror row_mask:0xf bank_mask:0xf bound_ctrl:1
	v_pk_fma_f32 v[44:45], v[190:191], v[78:79], v[76:77] op_sel_hi:[1,0,1]
	v_pk_fma_f32 v[42:43], v[188:189], v[78:79], v[74:75] op_sel_hi:[1,0,1]
	ds_read_b32 v176, v103 offset:19712
	ds_read_b128 v[164:167], v90 offset:18944
	ds_read_b128 v[172:175], v90 offset:19456
	s_waitcnt lgkmcnt(12)
	v_pk_mul_f32 v[72:73], v[44:45], v[54:55]
	v_pk_mul_f32 v[80:81], v[44:45], v[198:199]
	v_pk_fma_f32 v[72:73], v[42:43], v[52:53], v[72:73]
	v_pk_fma_f32 v[80:81], v[42:43], v[196:197], v[80:81]
	v_add_f32_e32 v78, v72, v73
	v_add_f32_e32 v241, v80, v81
	v_pk_mul_f32 v[74:75], v[42:43], v[56:57]
	v_add_f32_dpp v78, v78, v78 quad_perm:[1,0,3,2] row_mask:0xf bank_mask:0xf bound_ctrl:1
	v_pk_mul_f32 v[76:77], v[44:45], v[58:59]
	v_pk_fma_f32 v[74:75], v[200:201], v[64:65], v[74:75] op_sel_hi:[0,1,1]
	v_add_f32_dpp v78, v78, v78 quad_perm:[2,3,0,1] row_mask:0xf bank_mask:0xf bound_ctrl:1
	v_pk_fma_f32 v[76:77], v[200:201], v[66:67], v[76:77] op_sel_hi:[0,1,1]
	ds_read_b128 v[180:183], v90 offset:19968
	v_add_f32_dpp v78, v78, v78 row_half_mirror row_mask:0xf bank_mask:0xf bound_ctrl:1
	ds_read_b128 v[184:187], v90 offset:20224
	ds_read_b128 v[192:195], v90 offset:20736
	v_add_f32_dpp v78, v78, v78 row_mirror row_mask:0xf bank_mask:0xf bound_ctrl:1
	v_pk_fma_f32 v[44:45], v[62:63], v[78:79], v[76:77] op_sel_hi:[1,0,1]
	v_pk_fma_f32 v[42:43], v[60:61], v[78:79], v[74:75] op_sel_hi:[1,0,1]
	ds_read_b32 v178, v103 offset:21248
	ds_read_b128 v[188:191], v90 offset:20480
	ds_read_b128 v[196:199], v90 offset:20992
	s_waitcnt lgkmcnt(12)
	v_pk_mul_f32 v[72:73], v[44:45], v[212:213]
	v_pk_mul_f32 v[80:81], v[44:45], v[70:71]
	v_pk_fma_f32 v[72:73], v[42:43], v[210:211], v[72:73]
	v_pk_fma_f32 v[80:81], v[42:43], v[68:69], v[80:81]
	v_add_f32_e32 v78, v72, v73
	v_add_f32_e32 v242, v80, v81
	v_pk_mul_f32 v[74:75], v[42:43], v[214:215]
	v_add_f32_dpp v78, v78, v78 quad_perm:[1,0,3,2] row_mask:0xf bank_mask:0xf bound_ctrl:1
	v_pk_mul_f32 v[76:77], v[44:45], v[216:217]
	v_pk_fma_f32 v[74:75], v[230:231], v[222:223], v[74:75] op_sel_hi:[0,1,1]
	v_add_f32_dpp v78, v78, v78 quad_perm:[2,3,0,1] row_mask:0xf bank_mask:0xf bound_ctrl:1
	v_pk_fma_f32 v[76:77], v[230:231], v[224:225], v[76:77] op_sel_hi:[0,1,1]
	ds_read_b128 v[52:55], v90 offset:21504
	v_add_f32_dpp v78, v78, v78 row_half_mirror row_mask:0xf bank_mask:0xf bound_ctrl:1
	ds_read_b128 v[56:59], v90 offset:21760
	ds_read_b128 v[64:67], v90 offset:22272
	v_add_f32_dpp v78, v78, v78 row_mirror row_mask:0xf bank_mask:0xf bound_ctrl:1
	v_pk_fma_f32 v[44:45], v[220:221], v[78:79], v[76:77] op_sel_hi:[1,0,1]
	v_pk_fma_f32 v[42:43], v[218:219], v[78:79], v[74:75] op_sel_hi:[1,0,1]
	ds_read_b32 v200, v103 offset:22784
	ds_read_b128 v[60:63], v90 offset:22016
	ds_read_b128 v[68:71], v90 offset:22528
	s_waitcnt lgkmcnt(12)
	v_pk_mul_f32 v[72:73], v[44:45], v[158:159]
	v_pk_mul_f32 v[80:81], v[44:45], v[228:229]
	v_pk_fma_f32 v[72:73], v[42:43], v[156:157], v[72:73]
	v_pk_fma_f32 v[80:81], v[42:43], v[226:227], v[80:81]
	v_add_f32_e32 v78, v72, v73
	v_add_f32_e32 v243, v80, v81
	v_pk_mul_f32 v[74:75], v[42:43], v[160:161]
	v_add_f32_dpp v78, v78, v78 quad_perm:[1,0,3,2] row_mask:0xf bank_mask:0xf bound_ctrl:1
	v_pk_mul_f32 v[76:77], v[44:45], v[162:163]
	v_pk_fma_f32 v[74:75], v[176:177], v[168:169], v[74:75] op_sel_hi:[0,1,1]
	v_add_f32_dpp v78, v78, v78 quad_perm:[2,3,0,1] row_mask:0xf bank_mask:0xf bound_ctrl:1
	v_pk_fma_f32 v[76:77], v[176:177], v[170:171], v[76:77] op_sel_hi:[0,1,1]
	ds_read_b128 v[210:213], v90 offset:23040
	v_add_f32_dpp v78, v78, v78 row_half_mirror row_mask:0xf bank_mask:0xf bound_ctrl:1
	ds_read_b128 v[214:217], v90 offset:23296
	ds_read_b128 v[222:225], v90 offset:23808
	v_add_f32_dpp v78, v78, v78 row_mirror row_mask:0xf bank_mask:0xf bound_ctrl:1
	v_pk_fma_f32 v[44:45], v[166:167], v[78:79], v[76:77] op_sel_hi:[1,0,1]
	v_pk_fma_f32 v[42:43], v[164:165], v[78:79], v[74:75] op_sel_hi:[1,0,1]
	ds_read_b32 v230, v103 offset:24320
	ds_read_b128 v[218:221], v90 offset:23552
	ds_read_b128 v[226:229], v90 offset:24064
	s_waitcnt lgkmcnt(12)
	v_pk_mul_f32 v[72:73], v[44:45], v[182:183]
	v_pk_mul_f32 v[80:81], v[44:45], v[174:175]
	v_pk_fma_f32 v[72:73], v[42:43], v[180:181], v[72:73]
	v_pk_fma_f32 v[80:81], v[42:43], v[172:173], v[80:81]
	v_add_f32_e32 v78, v72, v73
	v_add_f32_e32 v244, v80, v81
	v_pk_mul_f32 v[74:75], v[42:43], v[184:185]
	v_add_f32_dpp v78, v78, v78 quad_perm:[1,0,3,2] row_mask:0xf bank_mask:0xf bound_ctrl:1
	v_pk_mul_f32 v[76:77], v[44:45], v[186:187]
	v_pk_fma_f32 v[74:75], v[178:179], v[192:193], v[74:75] op_sel_hi:[0,1,1]
	v_add_f32_dpp v78, v78, v78 quad_perm:[2,3,0,1] row_mask:0xf bank_mask:0xf bound_ctrl:1
	v_pk_fma_f32 v[76:77], v[178:179], v[194:195], v[76:77] op_sel_hi:[0,1,1]
	s_nop 0
	v_add_f32_dpp v78, v78, v78 row_half_mirror row_mask:0xf bank_mask:0xf bound_ctrl:1
	s_nop 0
	s_nop 0
	v_add_f32_dpp v78, v78, v78 row_mirror row_mask:0xf bank_mask:0xf bound_ctrl:1
	v_pk_fma_f32 v[44:45], v[190:191], v[78:79], v[76:77] op_sel_hi:[1,0,1]
	v_pk_fma_f32 v[42:43], v[188:189], v[78:79], v[74:75] op_sel_hi:[1,0,1]
	s_waitcnt lgkmcnt(6)
	v_pk_mul_f32 v[72:73], v[44:45], v[54:55]
	v_pk_mul_f32 v[80:81], v[44:45], v[198:199]
	v_pk_fma_f32 v[72:73], v[42:43], v[52:53], v[72:73]
	v_pk_fma_f32 v[80:81], v[42:43], v[196:197], v[80:81]
	v_add_f32_e32 v78, v72, v73
	v_add_f32_e32 v245, v80, v81
	v_pk_mul_f32 v[74:75], v[42:43], v[56:57]
	v_add_f32_dpp v78, v78, v78 quad_perm:[1,0,3,2] row_mask:0xf bank_mask:0xf bound_ctrl:1
	v_pk_mul_f32 v[76:77], v[44:45], v[58:59]
	v_pk_fma_f32 v[74:75], v[200:201], v[64:65], v[74:75] op_sel_hi:[0,1,1]
	v_add_f32_dpp v78, v78, v78 quad_perm:[2,3,0,1] row_mask:0xf bank_mask:0xf bound_ctrl:1
	v_pk_fma_f32 v[76:77], v[200:201], v[66:67], v[76:77] op_sel_hi:[0,1,1]
	s_nop 0
	v_add_f32_dpp v78, v78, v78 row_half_mirror row_mask:0xf bank_mask:0xf bound_ctrl:1
	s_nop 0
	s_nop 0
	v_add_f32_dpp v78, v78, v78 row_mirror row_mask:0xf bank_mask:0xf bound_ctrl:1
	v_pk_fma_f32 v[44:45], v[62:63], v[78:79], v[76:77] op_sel_hi:[1,0,1]
	v_pk_fma_f32 v[42:43], v[60:61], v[78:79], v[74:75] op_sel_hi:[1,0,1]
	s_waitcnt lgkmcnt(0)
	v_pk_mul_f32 v[72:73], v[44:45], v[212:213]
	v_pk_mul_f32 v[80:81], v[44:45], v[70:71]
	v_pk_fma_f32 v[72:73], v[42:43], v[210:211], v[72:73]
	v_pk_fma_f32 v[80:81], v[42:43], v[68:69], v[80:81]
	v_add_f32_e32 v78, v72, v73
	v_add_f32_e32 v246, v80, v81
	v_pk_mul_f32 v[74:75], v[42:43], v[214:215]
	v_add_f32_dpp v78, v78, v78 quad_perm:[1,0,3,2] row_mask:0xf bank_mask:0xf bound_ctrl:1
	v_pk_mul_f32 v[76:77], v[44:45], v[216:217]
	v_pk_fma_f32 v[74:75], v[230:231], v[222:223], v[74:75] op_sel_hi:[0,1,1]
	v_add_f32_dpp v78, v78, v78 quad_perm:[2,3,0,1] row_mask:0xf bank_mask:0xf bound_ctrl:1
	v_pk_fma_f32 v[76:77], v[230:231], v[224:225], v[76:77] op_sel_hi:[0,1,1]
	s_nop 0
	v_add_f32_dpp v78, v78, v78 row_half_mirror row_mask:0xf bank_mask:0xf bound_ctrl:1
	s_nop 0
	s_nop 0
	v_add_f32_dpp v78, v78, v78 row_mirror row_mask:0xf bank_mask:0xf bound_ctrl:1
	v_pk_fma_f32 v[44:45], v[220:221], v[78:79], v[76:77] op_sel_hi:[1,0,1]
	v_pk_fma_f32 v[42:43], v[218:219], v[78:79], v[74:75] op_sel_hi:[1,0,1]
	v_pk_mul_f32 v[80:81], v[44:45], v[228:229]
	s_nop 0
	v_pk_fma_f32 v[80:81], v[42:43], v[226:227], v[80:81]
	s_nop 0
	v_add_f32_e32 v247, v80, v81
	s_waitcnt vmcnt(1)
	v_and_b32_e32 v49, 0xffff0000, v27
	s_add_i32 s2, s7, 3
	s_cmp_ge_u32 s2, s19
	v_lshlrev_b32_e32 v46, 16, v26
	v_and_b32_e32 v47, 0xffff0000, v26
	v_lshlrev_b32_e32 v48, 16, v27
	ds_write_b128 v96, v[2:5] offset:24576
	ds_write_b128 v96, v[6:9] offset:30720
	ds_write_b128 v96, v[10:13] offset:36864
	ds_write_b128 v96, v[14:17] offset:43008
	ds_write_b128 v97, v[46:49] offset:25600
	v_lshlrev_b32_e32 v46, 16, v28
	v_and_b32_e32 v47, 0xffff0000, v28
	v_lshlrev_b32_e32 v48, 16, v29
	v_and_b32_e32 v49, 0xffff0000, v29
	ds_write_b128 v97, v[46:49] offset:25616
	s_cbranch_scc1 .LBB0_1255
	s_lshl_b32 s2, s2, 4
	v_add_u32_e32 v12, s2, v1
	v_xad_u32 v2, v12, -1, s18
	v_sub_u32_e32 v13, s18, v12
	v_cndmask_b32_e64 v2, v2, v12, s[16:17]
	v_add_u32_e32 v4, 4, v12
	v_add_u32_e32 v5, -5, v13
	v_add_u32_e32 v10, 8, v12
	v_add_u32_e32 v11, -9, v13
	v_add_u32_e32 v12, 12, v12
	v_add_u32_e32 v13, -13, v13
	v_readlane_b32 s4, v206, 6
	v_cndmask_b32_e64 v4, v5, v4, s[16:17]
	v_cndmask_b32_e64 v10, v11, v10, s[16:17]
	v_cndmask_b32_e64 v12, v13, v12, s[16:17]
	v_add_u32_e32 v26, s2, v91
	v_add_u32_e32 v2, s4, v2
	v_add_u32_e32 v4, s4, v4
	v_add_u32_e32 v10, s4, v10
	v_add_u32_e32 v12, s4, v12
	v_xad_u32 v27, v26, -1, s18
	v_ashrrev_i32_e32 v3, 31, v2
	v_ashrrev_i32_e32 v5, 31, v4
	v_ashrrev_i32_e32 v11, 31, v10
	v_ashrrev_i32_e32 v13, 31, v12
	v_cndmask_b32_e64 v26, v27, v26, s[16:17]
	v_lshlrev_b64 v[2:3], 10, v[2:3]
	v_lshlrev_b64 v[4:5], 10, v[4:5]
	v_lshlrev_b64 v[10:11], 10, v[10:11]
	v_lshlrev_b64 v[12:13], 10, v[12:13]
	v_add_u32_e32 v26, s4, v26
	v_lshl_add_u64 v[2:3], v[92:93], 0, v[2:3]
	v_lshl_add_u64 v[6:7], v[92:93], 0, v[4:5]
	v_lshl_add_u64 v[10:11], v[92:93], 0, v[10:11]
	v_lshl_add_u64 v[14:15], v[92:93], 0, v[12:13]
	v_mad_i64_i32 v[26:27], s[2:3], v26, s37, v[94:95]
	global_load_dwordx4 v[2:5], v[2:3], off
	s_nop 0
	global_load_dwordx4 v[6:9], v[6:7], off
	s_nop 0
	global_load_dwordx4 v[10:13], v[10:11], off
	s_nop 0
	global_load_dwordx4 v[14:17], v[14:15], off
	v_readlane_b32 s5, v206, 7
	global_load_dwordx4 v[26:29], v[26:27], off
.LBB0_1255:
	s_waitcnt lgkmcnt(0)
	s_barrier
	ds_read_b128 v[156:159], v90 offset:24576
	ds_read_b128 v[160:163], v90 offset:24832
	ds_read_b128 v[168:171], v90 offset:25344
	ds_read_b32 v176, v103 offset:25856
	ds_read_b128 v[164:167], v90 offset:25088
	ds_read_b128 v[172:175], v90 offset:25600
	ds_read_b128 v[180:183], v90 offset:26112
	ds_read_b128 v[184:187], v90 offset:26368
	ds_read_b128 v[192:195], v90 offset:26880
	ds_read_b32 v178, v103 offset:27392
	ds_read_b128 v[188:191], v90 offset:26624
	ds_read_b128 v[196:199], v90 offset:27136
	ds_read_b128 v[52:55], v90 offset:27648
	ds_read_b128 v[56:59], v90 offset:27904
	ds_read_b128 v[64:67], v90 offset:28416
	ds_read_b32 v200, v103 offset:28928
	ds_read_b128 v[60:63], v90 offset:28160
	ds_read_b128 v[68:71], v90 offset:28672
	s_mov_b32 s4, 0xcccccccc
	s_mov_b32 s5, 0xcccccccc
	s_mov_b32 s12, 0xaaaaaaaa
	s_mov_b32 s13, 0xaaaaaaaa
	v_add_f32_dpp v232, v232, v232 row_ror:8 row_mask:0xf bank_mask:0x3
	v_add_f32_dpp v233, v233, v233 row_ror:8 row_mask:0xf bank_mask:0x3
	v_add_f32_dpp v234, v234, v234 row_ror:8 row_mask:0xf bank_mask:0x3
	v_add_f32_dpp v235, v235, v235 row_ror:8 row_mask:0xf bank_mask:0x3
	v_add_f32_dpp v236, v236, v236 row_ror:8 row_mask:0xf bank_mask:0x3
	v_add_f32_dpp v237, v237, v237 row_ror:8 row_mask:0xf bank_mask:0x3
	v_add_f32_dpp v238, v238, v238 row_ror:8 row_mask:0xf bank_mask:0x3
	v_add_f32_dpp v239, v239, v239 row_ror:8 row_mask:0xf bank_mask:0x3
	v_add_f32_dpp v232, v240, v240 row_ror:8 row_mask:0xf bank_mask:0xc
	v_add_f32_dpp v233, v241, v241 row_ror:8 row_mask:0xf bank_mask:0xc
	v_add_f32_dpp v234, v242, v242 row_ror:8 row_mask:0xf bank_mask:0xc
	v_add_f32_dpp v235, v243, v243 row_ror:8 row_mask:0xf bank_mask:0xc
	v_add_f32_dpp v236, v244, v244 row_ror:8 row_mask:0xf bank_mask:0xc
	v_add_f32_dpp v237, v245, v245 row_ror:8 row_mask:0xf bank_mask:0xc
	v_add_f32_dpp v238, v246, v246 row_ror:8 row_mask:0xf bank_mask:0xc
	v_add_f32_dpp v239, v247, v247 row_ror:8 row_mask:0xf bank_mask:0xc
	v_add_f32_dpp v232, v232, v232 row_shl:4 row_mask:0xf bank_mask:0x5
	v_add_f32_dpp v233, v233, v233 row_shl:4 row_mask:0xf bank_mask:0x5
	v_add_f32_dpp v234, v234, v234 row_shl:4 row_mask:0xf bank_mask:0x5
	v_add_f32_dpp v235, v235, v235 row_shl:4 row_mask:0xf bank_mask:0x5
	v_add_f32_dpp v232, v236, v236 row_shr:4 row_mask:0xf bank_mask:0xa
	v_add_f32_dpp v233, v237, v237 row_shr:4 row_mask:0xf bank_mask:0xa
	v_add_f32_dpp v234, v238, v238 row_shr:4 row_mask:0xf bank_mask:0xa
	v_add_f32_dpp v235, v239, v239 row_shr:4 row_mask:0xf bank_mask:0xa
	v_add_f32_dpp v240, v232, v232 quad_perm:[2,3,0,1] row_mask:0xf bank_mask:0xf
	v_add_f32_dpp v241, v233, v233 quad_perm:[2,3,0,1] row_mask:0xf bank_mask:0xf
	v_add_f32_dpp v242, v234, v234 quad_perm:[2,3,0,1] row_mask:0xf bank_mask:0xf
	v_add_f32_dpp v243, v235, v235 quad_perm:[2,3,0,1] row_mask:0xf bank_mask:0xf
	v_cndmask_b32_e64 v236, v240, v242, s[4:5]
	v_cndmask_b32_e64 v237, v241, v243, s[4:5]
	s_nop 0
	v_add_f32_dpp v238, v236, v236 quad_perm:[1,0,3,2] row_mask:0xf bank_mask:0xf
	v_add_f32_dpp v239, v237, v237 quad_perm:[1,0,3,2] row_mask:0xf bank_mask:0xf
	v_cndmask_b32_e64 v249, v238, v239, s[12:13]
	s_mov_b32 s2, s7
	v_lshl_or_b32 v250, s2, 4, v87
	v_xad_u32 v251, v250, -1, s18
	s_nop 0
	v_cndmask_b32_e64 v250, v251, v250, s[16:17]
	v_ashrrev_i32_e32 v251, 31, v250
	v_lshlrev_b64 v[250:251], 10, v[250:251]
	v_lshl_add_u64 v[250:251], v[98:99], 0, v[250:251]
	global_store_dword v[250:251], v249, off
	s_waitcnt lgkmcnt(12)
	v_pk_mul_f32 v[72:73], v[44:45], v[158:159]
	v_pk_mul_f32 v[74:75], v[42:43], v[160:161]
	v_pk_fma_f32 v[72:73], v[42:43], v[156:157], v[72:73]
	v_pk_mul_f32 v[76:77], v[44:45], v[162:163]
	v_add_f32_e32 v78, v72, v73
	v_pk_fma_f32 v[74:75], v[176:177], v[168:169], v[74:75] op_sel_hi:[0,1,1]
	v_pk_fma_f32 v[76:77], v[176:177], v[170:171], v[76:77] op_sel_hi:[0,1,1]
	v_add_f32_dpp v78, v78, v78 quad_perm:[1,0,3,2] row_mask:0xf bank_mask:0xf bound_ctrl:1
	ds_read_b128 v[210:213], v90 offset:29184
	ds_read_b128 v[214:217], v90 offset:29440
	v_add_f32_dpp v78, v78, v78 quad_perm:[2,3,0,1] row_mask:0xf bank_mask:0xf bound_ctrl:1
	ds_read_b128 v[222:225], v90 offset:29952
	ds_read_b32 v230, v103 offset:30464
	v_add_f32_dpp v78, v78, v78 row_half_mirror row_mask:0xf bank_mask:0xf bound_ctrl:1
	ds_read_b128 v[218:221], v90 offset:29696
	ds_read_b128 v[226:229], v90 offset:30208
	v_add_f32_dpp v78, v78, v78 row_mirror row_mask:0xf bank_mask:0xf bound_ctrl:1
	v_pk_fma_f32 v[44:45], v[166:167], v[78:79], v[76:77] op_sel_hi:[1,0,1]
	v_pk_fma_f32 v[42:43], v[164:165], v[78:79], v[74:75] op_sel_hi:[1,0,1]
	s_waitcnt lgkmcnt(12)
	v_pk_mul_f32 v[72:73], v[44:45], v[182:183]
	v_pk_mul_f32 v[80:81], v[44:45], v[174:175]
	v_pk_fma_f32 v[72:73], v[42:43], v[180:181], v[72:73]
	v_pk_fma_f32 v[80:81], v[42:43], v[172:173], v[80:81]
	v_add_f32_e32 v78, v72, v73
	v_add_f32_e32 v232, v80, v81
	v_pk_mul_f32 v[74:75], v[42:43], v[184:185]
	v_add_f32_dpp v78, v78, v78 quad_perm:[1,0,3,2] row_mask:0xf bank_mask:0xf bound_ctrl:1
	v_pk_mul_f32 v[76:77], v[44:45], v[186:187]
	v_pk_fma_f32 v[74:75], v[178:179], v[192:193], v[74:75] op_sel_hi:[0,1,1]
	v_add_f32_dpp v78, v78, v78 quad_perm:[2,3,0,1] row_mask:0xf bank_mask:0xf bound_ctrl:1
	v_pk_fma_f32 v[76:77], v[178:179], v[194:195], v[76:77] op_sel_hi:[0,1,1]
	ds_read_b128 v[156:159], v90 offset:30720
	v_add_f32_dpp v78, v78, v78 row_half_mirror row_mask:0xf bank_mask:0xf bound_ctrl:1
	ds_read_b128 v[160:163], v90 offset:30976
	ds_read_b128 v[168:171], v90 offset:31488
	v_add_f32_dpp v78, v78, v78 row_mirror row_mask:0xf bank_mask:0xf bound_ctrl:1
	v_pk_fma_f32 v[44:45], v[190:191], v[78:79], v[76:77] op_sel_hi:[1,0,1]
	v_pk_fma_f32 v[42:43], v[188:189], v[78:79], v[74:75] op_sel_hi:[1,0,1]
	ds_read_b32 v176, v103 offset:32000
	ds_read_b128 v[164:167], v90 offset:31232
	ds_read_b128 v[172:175], v90 offset:31744
	s_waitcnt lgkmcnt(12)
	v_pk_mul_f32 v[72:73], v[44:45], v[54:55]
	v_pk_mul_f32 v[80:81], v[44:45], v[198:199]
	v_pk_fma_f32 v[72:73], v[42:43], v[52:53], v[72:73]
	v_pk_fma_f32 v[80:81], v[42:43], v[196:197], v[80:81]
	v_add_f32_e32 v78, v72, v73
	v_add_f32_e32 v233, v80, v81
	v_pk_mul_f32 v[74:75], v[42:43], v[56:57]
	v_add_f32_dpp v78, v78, v78 quad_perm:[1,0,3,2] row_mask:0xf bank_mask:0xf bound_ctrl:1
	v_pk_mul_f32 v[76:77], v[44:45], v[58:59]
	v_pk_fma_f32 v[74:75], v[200:201], v[64:65], v[74:75] op_sel_hi:[0,1,1]
	v_add_f32_dpp v78, v78, v78 quad_perm:[2,3,0,1] row_mask:0xf bank_mask:0xf bound_ctrl:1
	v_pk_fma_f32 v[76:77], v[200:201], v[66:67], v[76:77] op_sel_hi:[0,1,1]
	ds_read_b128 v[180:183], v90 offset:32256
	v_add_f32_dpp v78, v78, v78 row_half_mirror row_mask:0xf bank_mask:0xf bound_ctrl:1
	ds_read_b128 v[184:187], v90 offset:32512
	ds_read_b128 v[192:195], v90 offset:33024
	v_add_f32_dpp v78, v78, v78 row_mirror row_mask:0xf bank_mask:0xf bound_ctrl:1
	v_pk_fma_f32 v[44:45], v[62:63], v[78:79], v[76:77] op_sel_hi:[1,0,1]
	v_pk_fma_f32 v[42:43], v[60:61], v[78:79], v[74:75] op_sel_hi:[1,0,1]
	ds_read_b32 v178, v103 offset:33536
	ds_read_b128 v[188:191], v90 offset:32768
	ds_read_b128 v[196:199], v90 offset:33280
	s_waitcnt lgkmcnt(12)
	v_pk_mul_f32 v[72:73], v[44:45], v[212:213]
	v_pk_mul_f32 v[80:81], v[44:45], v[70:71]
	v_pk_fma_f32 v[72:73], v[42:43], v[210:211], v[72:73]
	v_pk_fma_f32 v[80:81], v[42:43], v[68:69], v[80:81]
	v_add_f32_e32 v78, v72, v73
	v_add_f32_e32 v234, v80, v81
	v_pk_mul_f32 v[74:75], v[42:43], v[214:215]
	v_add_f32_dpp v78, v78, v78 quad_perm:[1,0,3,2] row_mask:0xf bank_mask:0xf bound_ctrl:1
	v_pk_mul_f32 v[76:77], v[44:45], v[216:217]
	v_pk_fma_f32 v[74:75], v[230:231], v[222:223], v[74:75] op_sel_hi:[0,1,1]
	v_add_f32_dpp v78, v78, v78 quad_perm:[2,3,0,1] row_mask:0xf bank_mask:0xf bound_ctrl:1
	v_pk_fma_f32 v[76:77], v[230:231], v[224:225], v[76:77] op_sel_hi:[0,1,1]
	ds_read_b128 v[52:55], v90 offset:33792
	v_add_f32_dpp v78, v78, v78 row_half_mirror row_mask:0xf bank_mask:0xf bound_ctrl:1
	ds_read_b128 v[56:59], v90 offset:34048
	ds_read_b128 v[64:67], v90 offset:34560
	v_add_f32_dpp v78, v78, v78 row_mirror row_mask:0xf bank_mask:0xf bound_ctrl:1
	v_pk_fma_f32 v[44:45], v[220:221], v[78:79], v[76:77] op_sel_hi:[1,0,1]
	v_pk_fma_f32 v[42:43], v[218:219], v[78:79], v[74:75] op_sel_hi:[1,0,1]
	ds_read_b32 v200, v103 offset:35072
	ds_read_b128 v[60:63], v90 offset:34304
	ds_read_b128 v[68:71], v90 offset:34816
	s_waitcnt lgkmcnt(12)
	v_pk_mul_f32 v[72:73], v[44:45], v[158:159]
	v_pk_mul_f32 v[80:81], v[44:45], v[228:229]
	v_pk_fma_f32 v[72:73], v[42:43], v[156:157], v[72:73]
	v_pk_fma_f32 v[80:81], v[42:43], v[226:227], v[80:81]
	v_add_f32_e32 v78, v72, v73
	v_add_f32_e32 v235, v80, v81
	v_pk_mul_f32 v[74:75], v[42:43], v[160:161]
	v_add_f32_dpp v78, v78, v78 quad_perm:[1,0,3,2] row_mask:0xf bank_mask:0xf bound_ctrl:1
	v_pk_mul_f32 v[76:77], v[44:45], v[162:163]
	v_pk_fma_f32 v[74:75], v[176:177], v[168:169], v[74:75] op_sel_hi:[0,1,1]
	v_add_f32_dpp v78, v78, v78 quad_perm:[2,3,0,1] row_mask:0xf bank_mask:0xf bound_ctrl:1
	v_pk_fma_f32 v[76:77], v[176:177], v[170:171], v[76:77] op_sel_hi:[0,1,1]
	ds_read_b128 v[210:213], v90 offset:35328
	v_add_f32_dpp v78, v78, v78 row_half_mirror row_mask:0xf bank_mask:0xf bound_ctrl:1
	ds_read_b128 v[214:217], v90 offset:35584
	ds_read_b128 v[222:225], v90 offset:36096
	v_add_f32_dpp v78, v78, v78 row_mirror row_mask:0xf bank_mask:0xf bound_ctrl:1
	v_pk_fma_f32 v[44:45], v[166:167], v[78:79], v[76:77] op_sel_hi:[1,0,1]
	v_pk_fma_f32 v[42:43], v[164:165], v[78:79], v[74:75] op_sel_hi:[1,0,1]
	ds_read_b32 v230, v103 offset:36608
	ds_read_b128 v[218:221], v90 offset:35840
	ds_read_b128 v[226:229], v90 offset:36352
	s_waitcnt lgkmcnt(12)
	v_pk_mul_f32 v[72:73], v[44:45], v[182:183]
	v_pk_mul_f32 v[80:81], v[44:45], v[174:175]
	v_pk_fma_f32 v[72:73], v[42:43], v[180:181], v[72:73]
	v_pk_fma_f32 v[80:81], v[42:43], v[172:173], v[80:81]
	v_add_f32_e32 v78, v72, v73
	v_add_f32_e32 v236, v80, v81
	v_pk_mul_f32 v[74:75], v[42:43], v[184:185]
	v_add_f32_dpp v78, v78, v78 quad_perm:[1,0,3,2] row_mask:0xf bank_mask:0xf bound_ctrl:1
	v_pk_mul_f32 v[76:77], v[44:45], v[186:187]
	v_pk_fma_f32 v[74:75], v[178:179], v[192:193], v[74:75] op_sel_hi:[0,1,1]
	v_add_f32_dpp v78, v78, v78 quad_perm:[2,3,0,1] row_mask:0xf bank_mask:0xf bound_ctrl:1
	v_pk_fma_f32 v[76:77], v[178:179], v[194:195], v[76:77] op_sel_hi:[0,1,1]
	ds_read_b128 v[156:159], v90 offset:36864
	v_add_f32_dpp v78, v78, v78 row_half_mirror row_mask:0xf bank_mask:0xf bound_ctrl:1
	ds_read_b128 v[160:163], v90 offset:37120
	ds_read_b128 v[168:171], v90 offset:37632
	v_add_f32_dpp v78, v78, v78 row_mirror row_mask:0xf bank_mask:0xf bound_ctrl:1
	v_pk_fma_f32 v[44:45], v[190:191], v[78:79], v[76:77] op_sel_hi:[1,0,1]
	v_pk_fma_f32 v[42:43], v[188:189], v[78:79], v[74:75] op_sel_hi:[1,0,1]
	ds_read_b32 v176, v103 offset:38144
	ds_read_b128 v[164:167], v90 offset:37376
	ds_read_b128 v[172:175], v90 offset:37888
	s_waitcnt lgkmcnt(12)
	v_pk_mul_f32 v[72:73], v[44:45], v[54:55]
	v_pk_mul_f32 v[80:81], v[44:45], v[198:199]
	v_pk_fma_f32 v[72:73], v[42:43], v[52:53], v[72:73]
	v_pk_fma_f32 v[80:81], v[42:43], v[196:197], v[80:81]
	v_add_f32_e32 v78, v72, v73
	v_add_f32_e32 v237, v80, v81
	v_pk_mul_f32 v[74:75], v[42:43], v[56:57]
	v_add_f32_dpp v78, v78, v78 quad_perm:[1,0,3,2] row_mask:0xf bank_mask:0xf bound_ctrl:1
	v_pk_mul_f32 v[76:77], v[44:45], v[58:59]
	v_pk_fma_f32 v[74:75], v[200:201], v[64:65], v[74:75] op_sel_hi:[0,1,1]
	v_add_f32_dpp v78, v78, v78 quad_perm:[2,3,0,1] row_mask:0xf bank_mask:0xf bound_ctrl:1
	v_pk_fma_f32 v[76:77], v[200:201], v[66:67], v[76:77] op_sel_hi:[0,1,1]
	ds_read_b128 v[180:183], v90 offset:38400
	v_add_f32_dpp v78, v78, v78 row_half_mirror row_mask:0xf bank_mask:0xf bound_ctrl:1
	ds_read_b128 v[184:187], v90 offset:38656
	ds_read_b128 v[192:195], v90 offset:39168
	v_add_f32_dpp v78, v78, v78 row_mirror row_mask:0xf bank_mask:0xf bound_ctrl:1
	v_pk_fma_f32 v[44:45], v[62:63], v[78:79], v[76:77] op_sel_hi:[1,0,1]
	v_pk_fma_f32 v[42:43], v[60:61], v[78:79], v[74:75] op_sel_hi:[1,0,1]
	ds_read_b32 v178, v103 offset:39680
	ds_read_b128 v[188:191], v90 offset:38912
	ds_read_b128 v[196:199], v90 offset:39424
	s_waitcnt lgkmcnt(12)
	v_pk_mul_f32 v[72:73], v[44:45], v[212:213]
	v_pk_mul_f32 v[80:81], v[44:45], v[70:71]
	v_pk_fma_f32 v[72:73], v[42:43], v[210:211], v[72:73]
	v_pk_fma_f32 v[80:81], v[42:43], v[68:69], v[80:81]
	v_add_f32_e32 v78, v72, v73
	v_add_f32_e32 v238, v80, v81
	v_pk_mul_f32 v[74:75], v[42:43], v[214:215]
	v_add_f32_dpp v78, v78, v78 quad_perm:[1,0,3,2] row_mask:0xf bank_mask:0xf bound_ctrl:1
	v_pk_mul_f32 v[76:77], v[44:45], v[216:217]
	v_pk_fma_f32 v[74:75], v[230:231], v[222:223], v[74:75] op_sel_hi:[0,1,1]
	v_add_f32_dpp v78, v78, v78 quad_perm:[2,3,0,1] row_mask:0xf bank_mask:0xf bound_ctrl:1
	v_pk_fma_f32 v[76:77], v[230:231], v[224:225], v[76:77] op_sel_hi:[0,1,1]
	ds_read_b128 v[52:55], v90 offset:39936
	v_add_f32_dpp v78, v78, v78 row_half_mirror row_mask:0xf bank_mask:0xf bound_ctrl:1
	ds_read_b128 v[56:59], v90 offset:40192
	ds_read_b128 v[64:67], v90 offset:40704
	v_add_f32_dpp v78, v78, v78 row_mirror row_mask:0xf bank_mask:0xf bound_ctrl:1
	v_pk_fma_f32 v[44:45], v[220:221], v[78:79], v[76:77] op_sel_hi:[1,0,1]
	v_pk_fma_f32 v[42:43], v[218:219], v[78:79], v[74:75] op_sel_hi:[1,0,1]
	ds_read_b32 v200, v103 offset:41216
	ds_read_b128 v[60:63], v90 offset:40448
	ds_read_b128 v[68:71], v90 offset:40960
	s_waitcnt lgkmcnt(12)
	v_pk_mul_f32 v[72:73], v[44:45], v[158:159]
	v_pk_mul_f32 v[80:81], v[44:45], v[228:229]
	v_pk_fma_f32 v[72:73], v[42:43], v[156:157], v[72:73]
	v_pk_fma_f32 v[80:81], v[42:43], v[226:227], v[80:81]
	v_add_f32_e32 v78, v72, v73
	v_add_f32_e32 v239, v80, v81
	v_pk_mul_f32 v[74:75], v[42:43], v[160:161]
	v_add_f32_dpp v78, v78, v78 quad_perm:[1,0,3,2] row_mask:0xf bank_mask:0xf bound_ctrl:1
	v_pk_mul_f32 v[76:77], v[44:45], v[162:163]
	v_pk_fma_f32 v[74:75], v[176:177], v[168:169], v[74:75] op_sel_hi:[0,1,1]
	v_add_f32_dpp v78, v78, v78 quad_perm:[2,3,0,1] row_mask:0xf bank_mask:0xf bound_ctrl:1
	v_pk_fma_f32 v[76:77], v[176:177], v[170:171], v[76:77] op_sel_hi:[0,1,1]
	ds_read_b128 v[210:213], v90 offset:41472
	v_add_f32_dpp v78, v78, v78 row_half_mirror row_mask:0xf bank_mask:0xf bound_ctrl:1
	ds_read_b128 v[214:217], v90 offset:41728
	ds_read_b128 v[222:225], v90 offset:42240
	v_add_f32_dpp v78, v78, v78 row_mirror row_mask:0xf bank_mask:0xf bound_ctrl:1
	v_pk_fma_f32 v[44:45], v[166:167], v[78:79], v[76:77] op_sel_hi:[1,0,1]
	v_pk_fma_f32 v[42:43], v[164:165], v[78:79], v[74:75] op_sel_hi:[1,0,1]
	ds_read_b32 v230, v103 offset:42752
	ds_read_b128 v[218:221], v90 offset:41984
	ds_read_b128 v[226:229], v90 offset:42496
	s_waitcnt lgkmcnt(12)
	v_pk_mul_f32 v[72:73], v[44:45], v[182:183]
	v_pk_mul_f32 v[80:81], v[44:45], v[174:175]
	v_pk_fma_f32 v[72:73], v[42:43], v[180:181], v[72:73]
	v_pk_fma_f32 v[80:81], v[42:43], v[172:173], v[80:81]
	v_add_f32_e32 v78, v72, v73
	v_add_f32_e32 v240, v80, v81
	v_pk_mul_f32 v[74:75], v[42:43], v[184:185]
	v_add_f32_dpp v78, v78, v78 quad_perm:[1,0,3,2] row_mask:0xf bank_mask:0xf bound_ctrl:1
	v_pk_mul_f32 v[76:77], v[44:45], v[186:187]
	v_pk_fma_f32 v[74:75], v[178:179], v[192:193], v[74:75] op_sel_hi:[0,1,1]
	v_add_f32_dpp v78, v78, v78 quad_perm:[2,3,0,1] row_mask:0xf bank_mask:0xf bound_ctrl:1
	v_pk_fma_f32 v[76:77], v[178:179], v[194:195], v[76:77] op_sel_hi:[0,1,1]
	ds_read_b128 v[156:159], v90 offset:43008
	v_add_f32_dpp v78, v78, v78 row_half_mirror row_mask:0xf bank_mask:0xf bound_ctrl:1
	ds_read_b128 v[160:163], v90 offset:43264
	ds_read_b128 v[168:171], v90 offset:43776
	v_add_f32_dpp v78, v78, v78 row_mirror row_mask:0xf bank_mask:0xf bound_ctrl:1
	v_pk_fma_f32 v[44:45], v[190:191], v[78:79], v[76:77] op_sel_hi:[1,0,1]
	v_pk_fma_f32 v[42:43], v[188:189], v[78:79], v[74:75] op_sel_hi:[1,0,1]
	ds_read_b32 v176, v103 offset:44288
	ds_read_b128 v[164:167], v90 offset:43520
	ds_read_b128 v[172:175], v90 offset:44032
	s_waitcnt lgkmcnt(12)
	v_pk_mul_f32 v[72:73], v[44:45], v[54:55]
	v_pk_mul_f32 v[80:81], v[44:45], v[198:199]
	v_pk_fma_f32 v[72:73], v[42:43], v[52:53], v[72:73]
	v_pk_fma_f32 v[80:81], v[42:43], v[196:197], v[80:81]
	v_add_f32_e32 v78, v72, v73
	v_add_f32_e32 v241, v80, v81
	v_pk_mul_f32 v[74:75], v[42:43], v[56:57]
	v_add_f32_dpp v78, v78, v78 quad_perm:[1,0,3,2] row_mask:0xf bank_mask:0xf bound_ctrl:1
	v_pk_mul_f32 v[76:77], v[44:45], v[58:59]
	v_pk_fma_f32 v[74:75], v[200:201], v[64:65], v[74:75] op_sel_hi:[0,1,1]
	v_add_f32_dpp v78, v78, v78 quad_perm:[2,3,0,1] row_mask:0xf bank_mask:0xf bound_ctrl:1
	v_pk_fma_f32 v[76:77], v[200:201], v[66:67], v[76:77] op_sel_hi:[0,1,1]
	ds_read_b128 v[180:183], v90 offset:44544
	v_add_f32_dpp v78, v78, v78 row_half_mirror row_mask:0xf bank_mask:0xf bound_ctrl:1
	ds_read_b128 v[184:187], v90 offset:44800
	ds_read_b128 v[192:195], v90 offset:45312
	v_add_f32_dpp v78, v78, v78 row_mirror row_mask:0xf bank_mask:0xf bound_ctrl:1
	v_pk_fma_f32 v[44:45], v[62:63], v[78:79], v[76:77] op_sel_hi:[1,0,1]
	v_pk_fma_f32 v[42:43], v[60:61], v[78:79], v[74:75] op_sel_hi:[1,0,1]
	ds_read_b32 v178, v103 offset:45824
	ds_read_b128 v[188:191], v90 offset:45056
	ds_read_b128 v[196:199], v90 offset:45568
	s_waitcnt lgkmcnt(12)
	v_pk_mul_f32 v[72:73], v[44:45], v[212:213]
	v_pk_mul_f32 v[80:81], v[44:45], v[70:71]
	v_pk_fma_f32 v[72:73], v[42:43], v[210:211], v[72:73]
	v_pk_fma_f32 v[80:81], v[42:43], v[68:69], v[80:81]
	v_add_f32_e32 v78, v72, v73
	v_add_f32_e32 v242, v80, v81
	v_pk_mul_f32 v[74:75], v[42:43], v[214:215]
	v_add_f32_dpp v78, v78, v78 quad_perm:[1,0,3,2] row_mask:0xf bank_mask:0xf bound_ctrl:1
	v_pk_mul_f32 v[76:77], v[44:45], v[216:217]
	v_pk_fma_f32 v[74:75], v[230:231], v[222:223], v[74:75] op_sel_hi:[0,1,1]
	v_add_f32_dpp v78, v78, v78 quad_perm:[2,3,0,1] row_mask:0xf bank_mask:0xf bound_ctrl:1
	v_pk_fma_f32 v[76:77], v[230:231], v[224:225], v[76:77] op_sel_hi:[0,1,1]
	ds_read_b128 v[52:55], v90 offset:46080
	v_add_f32_dpp v78, v78, v78 row_half_mirror row_mask:0xf bank_mask:0xf bound_ctrl:1
	ds_read_b128 v[56:59], v90 offset:46336
	ds_read_b128 v[64:67], v90 offset:46848
	v_add_f32_dpp v78, v78, v78 row_mirror row_mask:0xf bank_mask:0xf bound_ctrl:1
	v_pk_fma_f32 v[44:45], v[220:221], v[78:79], v[76:77] op_sel_hi:[1,0,1]
	v_pk_fma_f32 v[42:43], v[218:219], v[78:79], v[74:75] op_sel_hi:[1,0,1]
	ds_read_b32 v200, v103 offset:47360
	ds_read_b128 v[60:63], v90 offset:46592
	ds_read_b128 v[68:71], v90 offset:47104
	s_waitcnt lgkmcnt(12)
	v_pk_mul_f32 v[72:73], v[44:45], v[158:159]
	v_pk_mul_f32 v[80:81], v[44:45], v[228:229]
	v_pk_fma_f32 v[72:73], v[42:43], v[156:157], v[72:73]
	v_pk_fma_f32 v[80:81], v[42:43], v[226:227], v[80:81]
	v_add_f32_e32 v78, v72, v73
	v_add_f32_e32 v243, v80, v81
	v_pk_mul_f32 v[74:75], v[42:43], v[160:161]
	v_add_f32_dpp v78, v78, v78 quad_perm:[1,0,3,2] row_mask:0xf bank_mask:0xf bound_ctrl:1
	v_pk_mul_f32 v[76:77], v[44:45], v[162:163]
	v_pk_fma_f32 v[74:75], v[176:177], v[168:169], v[74:75] op_sel_hi:[0,1,1]
	v_add_f32_dpp v78, v78, v78 quad_perm:[2,3,0,1] row_mask:0xf bank_mask:0xf bound_ctrl:1
	v_pk_fma_f32 v[76:77], v[176:177], v[170:171], v[76:77] op_sel_hi:[0,1,1]
	ds_read_b128 v[210:213], v90 offset:47616
	v_add_f32_dpp v78, v78, v78 row_half_mirror row_mask:0xf bank_mask:0xf bound_ctrl:1
	ds_read_b128 v[214:217], v90 offset:47872
	ds_read_b128 v[222:225], v90 offset:48384
	v_add_f32_dpp v78, v78, v78 row_mirror row_mask:0xf bank_mask:0xf bound_ctrl:1
	v_pk_fma_f32 v[44:45], v[166:167], v[78:79], v[76:77] op_sel_hi:[1,0,1]
	v_pk_fma_f32 v[42:43], v[164:165], v[78:79], v[74:75] op_sel_hi:[1,0,1]
	ds_read_b32 v230, v103 offset:48896
	ds_read_b128 v[218:221], v90 offset:48128
	ds_read_b128 v[226:229], v90 offset:48640
	s_waitcnt lgkmcnt(12)
	v_pk_mul_f32 v[72:73], v[44:45], v[182:183]
	v_pk_mul_f32 v[80:81], v[44:45], v[174:175]
	v_pk_fma_f32 v[72:73], v[42:43], v[180:181], v[72:73]
	v_pk_fma_f32 v[80:81], v[42:43], v[172:173], v[80:81]
	v_add_f32_e32 v78, v72, v73
	v_add_f32_e32 v244, v80, v81
	v_pk_mul_f32 v[74:75], v[42:43], v[184:185]
	v_add_f32_dpp v78, v78, v78 quad_perm:[1,0,3,2] row_mask:0xf bank_mask:0xf bound_ctrl:1
	v_pk_mul_f32 v[76:77], v[44:45], v[186:187]
	v_pk_fma_f32 v[74:75], v[178:179], v[192:193], v[74:75] op_sel_hi:[0,1,1]
	v_add_f32_dpp v78, v78, v78 quad_perm:[2,3,0,1] row_mask:0xf bank_mask:0xf bound_ctrl:1
	v_pk_fma_f32 v[76:77], v[178:179], v[194:195], v[76:77] op_sel_hi:[0,1,1]
	s_nop 0
	v_add_f32_dpp v78, v78, v78 row_half_mirror row_mask:0xf bank_mask:0xf bound_ctrl:1
	s_nop 0
	s_nop 0
	v_add_f32_dpp v78, v78, v78 row_mirror row_mask:0xf bank_mask:0xf bound_ctrl:1
	v_pk_fma_f32 v[44:45], v[190:191], v[78:79], v[76:77] op_sel_hi:[1,0,1]
	v_pk_fma_f32 v[42:43], v[188:189], v[78:79], v[74:75] op_sel_hi:[1,0,1]
	s_waitcnt lgkmcnt(6)
	v_pk_mul_f32 v[72:73], v[44:45], v[54:55]
	v_pk_mul_f32 v[80:81], v[44:45], v[198:199]
	v_pk_fma_f32 v[72:73], v[42:43], v[52:53], v[72:73]
	v_pk_fma_f32 v[80:81], v[42:43], v[196:197], v[80:81]
	v_add_f32_e32 v78, v72, v73
	v_add_f32_e32 v245, v80, v81
	v_pk_mul_f32 v[74:75], v[42:43], v[56:57]
	v_add_f32_dpp v78, v78, v78 quad_perm:[1,0,3,2] row_mask:0xf bank_mask:0xf bound_ctrl:1
	v_pk_mul_f32 v[76:77], v[44:45], v[58:59]
	v_pk_fma_f32 v[74:75], v[200:201], v[64:65], v[74:75] op_sel_hi:[0,1,1]
	v_add_f32_dpp v78, v78, v78 quad_perm:[2,3,0,1] row_mask:0xf bank_mask:0xf bound_ctrl:1
	v_pk_fma_f32 v[76:77], v[200:201], v[66:67], v[76:77] op_sel_hi:[0,1,1]
	s_nop 0
	v_add_f32_dpp v78, v78, v78 row_half_mirror row_mask:0xf bank_mask:0xf bound_ctrl:1
	s_nop 0
	s_nop 0
	v_add_f32_dpp v78, v78, v78 row_mirror row_mask:0xf bank_mask:0xf bound_ctrl:1
	v_pk_fma_f32 v[44:45], v[62:63], v[78:79], v[76:77] op_sel_hi:[1,0,1]
	v_pk_fma_f32 v[42:43], v[60:61], v[78:79], v[74:75] op_sel_hi:[1,0,1]
	s_waitcnt lgkmcnt(0)
	v_pk_mul_f32 v[72:73], v[44:45], v[212:213]
	v_pk_mul_f32 v[80:81], v[44:45], v[70:71]
	v_pk_fma_f32 v[72:73], v[42:43], v[210:211], v[72:73]
	v_pk_fma_f32 v[80:81], v[42:43], v[68:69], v[80:81]
	v_add_f32_e32 v78, v72, v73
	v_add_f32_e32 v246, v80, v81
	v_pk_mul_f32 v[74:75], v[42:43], v[214:215]
	v_add_f32_dpp v78, v78, v78 quad_perm:[1,0,3,2] row_mask:0xf bank_mask:0xf bound_ctrl:1
	v_pk_mul_f32 v[76:77], v[44:45], v[216:217]
	v_pk_fma_f32 v[74:75], v[230:231], v[222:223], v[74:75] op_sel_hi:[0,1,1]
	v_add_f32_dpp v78, v78, v78 quad_perm:[2,3,0,1] row_mask:0xf bank_mask:0xf bound_ctrl:1
	v_pk_fma_f32 v[76:77], v[230:231], v[224:225], v[76:77] op_sel_hi:[0,1,1]
	s_nop 0
	v_add_f32_dpp v78, v78, v78 row_half_mirror row_mask:0xf bank_mask:0xf bound_ctrl:1
	s_nop 0
	s_nop 0
	v_add_f32_dpp v78, v78, v78 row_mirror row_mask:0xf bank_mask:0xf bound_ctrl:1
	v_pk_fma_f32 v[44:45], v[220:221], v[78:79], v[76:77] op_sel_hi:[1,0,1]
	v_pk_fma_f32 v[42:43], v[218:219], v[78:79], v[74:75] op_sel_hi:[1,0,1]
	v_pk_mul_f32 v[80:81], v[44:45], v[228:229]
	s_nop 0
	v_pk_fma_f32 v[80:81], v[42:43], v[226:227], v[80:81]
	s_nop 0
	v_add_f32_e32 v247, v80, v81
	s_add_i32 s10, s7, 2
	s_cmp_ge_u32 s10, s19
	s_cselect_b64 s[2:3], -1, 0
	s_and_b64 vcc, exec, s[2:3]
	s_cbranch_vccnz .LBB0_1259
	s_waitcnt vmcnt(2)
	v_lshlrev_b32_e32 v46, 16, v38
	v_and_b32_e32 v47, 0xffff0000, v38
	v_lshlrev_b32_e32 v48, 16, v39
	v_and_b32_e32 v49, 0xffff0000, v39
	ds_write_b128 v96, v[18:21]
	ds_write_b128 v96, v[22:25] offset:6144
	ds_write_b128 v96, v[30:33] offset:12288
	ds_write_b128 v96, v[34:37] offset:18432
	ds_write_b128 v97, v[46:49] offset:1024
	v_lshlrev_b32_e32 v46, 16, v40
	v_and_b32_e32 v47, 0xffff0000, v40
	v_lshlrev_b32_e32 v48, 16, v41
	v_and_b32_e32 v49, 0xffff0000, v41
	ds_write_b128 v97, v[46:49] offset:1040

	.amdhsa_kernel _Z14fwd_megakernel6Params
		.amdhsa_group_segment_fixed_size 49168
		.amdhsa_private_segment_fixed_size 0
		.amdhsa_kernarg_size 840
		.amdhsa_user_sgpr_count 2
		.amdhsa_user_sgpr_dispatch_ptr 0
		.amdhsa_user_sgpr_queue_ptr 0
		.amdhsa_user_sgpr_kernarg_segment_ptr 1
		.amdhsa_user_sgpr_dispatch_id 0
		.amdhsa_user_sgpr_kernarg_preload_length 0
		.amdhsa_user_sgpr_kernarg_preload_offset 0
		.amdhsa_user_sgpr_private_segment_size 0
		.amdhsa_uses_dynamic_stack 0
		.amdhsa_enable_private_segment 0
		.amdhsa_system_sgpr_workgroup_id_x 1
		.amdhsa_system_sgpr_workgroup_id_y 0
		.amdhsa_system_sgpr_workgroup_id_z 0
		.amdhsa_system_sgpr_workgroup_info 0
		.amdhsa_system_vgpr_workitem_id 0
		.amdhsa_next_free_vgpr 256
		.amdhsa_next_free_sgpr 100
		.amdhsa_accum_offset 256
		.amdhsa_reserve_vcc 1
		.amdhsa_float_round_mode_32 0
		.amdhsa_float_round_mode_16_64 0
		.amdhsa_float_denorm_mode_32 3
		.amdhsa_float_denorm_mode_16_64 3
		.amdhsa_dx10_clamp 1
		.amdhsa_ieee_mode 1
		.amdhsa_fp16_overflow 0
		.amdhsa_tg_split 0
		.amdhsa_exception_fp_ieee_invalid_op 0
		.amdhsa_exception_fp_denorm_src 0
		.amdhsa_exception_fp_ieee_div_zero 0
		.amdhsa_exception_fp_ieee_overflow 0
		.amdhsa_exception_fp_ieee_underflow 0
		.amdhsa_exception_fp_ieee_inexact 0
		.amdhsa_exception_int_div_zero 0
	.end_amdhsa_kernel

amdhsa.kernels:
  - .agpr_count:     0
    .args:
      - .offset:         0
        .size:           584
        .value_kind:     by_value
      - .offset:         584
        .size:           4
        .value_kind:     hidden_block_count_x
      - .offset:         588
        .size:           4
        .value_kind:     hidden_block_count_y
      - .offset:         592
        .size:           4
        .value_kind:     hidden_block_count_z
      - .offset:         596
        .size:           2
        .value_kind:     hidden_group_size_x
      - .offset:         598
        .size:           2
        .value_kind:     hidden_group_size_y
      - .offset:         600
        .size:           2
        .value_kind:     hidden_group_size_z
      - .offset:         602
        .size:           2
        .value_kind:     hidden_remainder_x
      - .offset:         604
        .size:           2
        .value_kind:     hidden_remainder_y
      - .offset:         606
        .size:           2
        .value_kind:     hidden_remainder_z
      - .offset:         624
        .size:           8
        .value_kind:     hidden_global_offset_x
      - .offset:         632
        .size:           8
        .value_kind:     hidden_global_offset_y
      - .offset:         640
        .size:           8
        .value_kind:     hidden_global_offset_z
      - .offset:         648
        .size:           2
        .value_kind:     hidden_grid_dims
    .group_segment_fixed_size: 49168
    .kernarg_segment_align: 8
    .kernarg_segment_size: 840
    .language:       OpenCL C
    .language_version:
      - 2
      - 0
    .max_flat_workgroup_size: 256
    .name:           _Z14fwd_megakernel6Params
    .private_segment_fixed_size: 0
    .sgpr_count:     106
    .sgpr_spill_count: 452
    .symbol:         _Z14fwd_megakernel6Params.kd
    .uniform_work_group_size: 1
    .uses_dynamic_stack: false
    .vgpr_count:     256
    .vgpr_spill_count: 0
    .wavefront_size: 64
